# speedup vs baseline: 1.0081x; 1.0081x over previous
; #define WAIT_V(n) asm volatile("s_waitcnt vmcnt(" #n ")" ::: "memory")
; #define BAR __builtin_amdgcn_s_barrier()
;     ...
;   for (int vw = blockIdx.x; vw < nwg; vw += gridDim.x) {
;     int tid_ = threadIdx.x;
;     asm volatile("" : "+v"(tid_));
;     const int wid = tid_ >> 6, lane = tid_ & 63, wr = wid >> 2, wc = wid & 3, fr = lane & 15, fq = lane >> 4;
;     int brow, bcol;
;     TILE_COORDS(vw, brow, bcol);
;     f32x4 acc[2][2][4][2] = {};
;     bf16x8 At[4][2], B0[2][2], B1[2][2];
;     STAGE(SB(0, 0), Bt, bcol, 0); STAGE(SA(0, 0), A, brow, 0);
;     STAGE(SB(0, 1), Bt, bcol + HALF, 0); STAGE(SA(0, 1), A, brow + HALF, 0);
;     if (wr == 1) BAR;
;     WAIT_V(4); BAR;
;     STAGE(SB(1, 0), Bt, bcol, 1); STAGE(SA(1, 0), A, brow, 1); STAGE(SB(1, 1), Bt, bcol + HALF, 1);
;     WAIT_V(6); BAR;
;     for (int t = 0; t < nt - 2; t += 2) {
.LBB0_540:
	s_or_b64 exec, exec, s[2:3]
	s_cmpk_gt_i32 s60, 0xfff
	s_barrier
	s_cbranch_scc1 .LBB0_553
	s_add_i32 s19, 0, 0x10000
	s_add_i32 s21, 0, 0x14000
	s_mov_b64 s[2:3], 0x80
	s_add_i32 s30, 0, 0x18000
	s_add_i32 s31, 0, 0x1c000
	s_movk_i32 s33, 0x3c0
	s_mov_b64 s[6:7], 0x80080
	s_mov_b64 s[8:9], 0x100
	s_mov_b64 s[10:11], 0x80100
	s_mov_b64 s[12:13], 0x180
	s_mov_b64 s[14:15], 0x80180
	s_mov_b64 s[16:17], 0xf80
	s_movk_i32 s34, 0x100
	s_movk_i32 s35, 0x210
	s_mov_b32 s18, 0x3a000000
	s_mov_b32 s20, 0x358637bd
	s_mov_b32 s36, 0x800000
	v_mov_b32_e32 v145, 0
	v_mov_b32_e32 v150, 1
	s_mov_b32 s37, s60
	s_waitcnt vmcnt(0)
	s_mov_b32 s32, 0
	v_writelane_b32 v255, s62, 12
	v_writelane_b32 v255, s63, 13
	v_writelane_b32 v255, s64, 14
	v_writelane_b32 v255, s65, 15
	v_writelane_b32 v255, s66, 16
	v_writelane_b32 v255, s67, 17
	v_writelane_b32 v255, s68, 18
	v_writelane_b32 v255, s69, 19
	v_writelane_b32 v255, s70, 20
	v_writelane_b32 v255, s71, 21
	v_writelane_b32 v255, s72, 22
	v_writelane_b32 v255, s73, 23
	s_branch .LBB0_543
.LBB0_542:
	s_or_b64 exec, exec, s[4:5]
	s_mov_b32 s70, s24
	s_mov_b32 s71, s22
	s_add_i32 s37, s37, s61
	s_cmpk_lt_i32 s37, 0x1000
	s_cbranch_scc0 .Lp6_lasttile
	s_mov_b32 s32, 1
	s_branch .LBB0_543

;     ...
;           if (MODE == 3) {
;             const long row = brow + rloc;
;             const float4 s0 = *(const float4*)(ssq + row * 8), s1 = *(const float4*)(ssq + row * 8 + 4);
;             rscale = rsqrtf((s0.x + s0.y + s0.z + s0.w + s1.x + s1.y + s1.z + s1.w) * (1.f / DM) + EPS);
.Lp6_epi:
	s_cmp_eq_u32 s32, 2
	s_cbranch_scc1 .Lp6_sw0
	s_waitcnt vmcnt(8)
	s_branch .Lp6_sw1

;     ...
;     if (MODE == 0 || MODE == 3) {
;       char* ct = smem;
; #pragma unroll
;       for (int ai = 0; ai < 2; ++ai)
; #pragma unroll
;         for (int m = 0; m < 4; ++m) {
;           const int rloc = ai * HALF + wr * 64 + m * 16 + fr;
;           float rscale = 1.f;
;           if (MODE == 3) {
;             const long row = brow + rloc;
;             const float4 s0 = *(const float4*)(ssq + row * 8), s1 = *(const float4*)(ssq + row * 8 + 4);
;             rscale = rsqrtf((s0.x + s0.y + s0.z + s0.w + s1.x + s1.y + s1.z + s1.w) * (1.f / DM) + EPS);
;           }
; #pragma unroll
;           for (int bj = 0; bj < 2; ++bj)
; #pragma unroll
;             for (int n = 0; n < 2; ++n) {
;               const int cl = bj * HALF + wc * 32 + n * 16 + fq * 4;
;               f32x4 a = acc[ai][bj][m][n];
;               uint2 o;
;               o.x = pack2(a[0] * rscale, a[1] * rscale);
;               o.y = pack2(a[2] * rscale, a[3] * rscale);
;               *(uint2*)(ct + rloc * 528 + cl * 2) = o;
.Lp6_sw1:
	v_add_f32_e32 v250, v250, v251
	v_add_f32_e32 v250, v250, v252
	v_add_f32_e32 v250, v250, v253
	v_and_b32_e32 v251, 0xff, v194
	v_lshrrev_b32_e32 v252, 8, v194
	v_lshl_or_b32 v251, v251, 1, v252
	v_lshlrev_b32_e32 v251, 2, v251
	v_add_u32_e32 v251, 0x20400, v251
	ds_write_b32 v251, v250
	v_and_b32_e32 v170, 15, v194
	v_bfe_u32 v171, v194, 4, 2
	v_bfe_u32 v172, v194, 6, 2
	v_mul_u32_u24_e32 v173, 0x210, v170
	v_lshlrev_b32_e32 v174, 6, v172
	v_lshl_add_u32 v174, v171, 3, v174
	v_add_u32_e32 v184, v173, v174
	v_add_u32_e32 v184, 0x18000, v184
	v_add_u32_e32 v185, 0x2100, v184
	v_add_u32_e32 v186, 0x4200, v184
	v_add_u32_e32 v187, 0x6300, v184
	v_lshlrev_b32_e32 v179, 3, v170
	v_add_u32_e32 v179, 0x20400, v179
	v_lshrrev_b32_e32 v175, 5, v194
	v_and_b32_e32 v176, 31, v194
	v_mul_u32_u24_e32 v177, 0x210, v175
	v_lshl_add_u32 v177, v176, 4, v177
	v_add_u32_e32 v177, 0x18000, v177
	v_readfirstlane_b32 s62, v194
	s_lshl_b32 s66, s71, 1
	s_add_u32 s66, s88, s66
	s_addc_u32 s67, s89, 0
	s_lshr_b32 s62, s62, 8
	v_add_u32_e32 v178, s70, v175
	v_lshlrev_b32_e32 v180, 4, v176
	v_mov_b32_e32 v181, 0
	v_lshl_add_u64 v[180:181], s[66:67], 0, v[180:181]
	s_movk_i32 s63, 0x4000
	v_mad_u64_u32 v[182:183], s[68:69], v178, s63, v[180:181]
	s_mov_b32 s72, 0x40000
	s_mov_b32 s73, 0
	s_waitcnt lgkmcnt(0)
	s_barrier
	s_cmp_lg_u32 s62, 0
	s_cbranch_scc1 .Lp6_q0r
	ds_read_b64 v[188:189], v179
	ds_read_b64 v[190:191], v179 offset:128
	ds_read_b64 v[192:193], v179 offset:256
	ds_read_b64 v[196:197], v179 offset:384
	s_waitcnt lgkmcnt(0)
	v_add_f32_e32 v188, v188, v189
	v_mul_f32_e32 v188, 0x3a000000, v188
	v_add_f32_e32 v188, 0x358637bd, v188
	v_rsq_f32_e32 v188, v188
	v_add_f32_e32 v190, v190, v191
	v_mul_f32_e32 v190, 0x3a000000, v190
	v_add_f32_e32 v190, 0x358637bd, v190
	v_rsq_f32_e32 v190, v190
	v_add_f32_e32 v192, v192, v193
	v_mul_f32_e32 v192, 0x3a000000, v192
	v_add_f32_e32 v192, 0x358637bd, v192
	v_rsq_f32_e32 v192, v192
	v_add_f32_e32 v196, v196, v197
	v_mul_f32_e32 v196, 0x3a000000, v196
	v_add_f32_e32 v196, 0x358637bd, v196
	v_rsq_f32_e32 v196, v196
	s_nop 0
	v_mul_f32_e32 v104, v104, v188
	v_mul_f32_e32 v105, v105, v188
	v_mul_f32_e32 v106, v106, v188
	v_mul_f32_e32 v107, v107, v188
	v_cvt_pk_bf16_f32 v104, v104, v105
	v_cvt_pk_bf16_f32 v105, v106, v107
	v_mul_f32_e32 v108, v108, v188
	v_mul_f32_e32 v109, v109, v188
	v_mul_f32_e32 v110, v110, v188
	v_mul_f32_e32 v111, v111, v188
	v_cvt_pk_bf16_f32 v108, v108, v109
	v_cvt_pk_bf16_f32 v109, v110, v111
	ds_write2_b64 v184, v[104:105], v[108:109] offset1:4
	v_mul_f32_e32 v120, v120, v188
	v_mul_f32_e32 v121, v121, v188
	v_mul_f32_e32 v122, v122, v188
	v_mul_f32_e32 v123, v123, v188
	v_cvt_pk_bf16_f32 v120, v120, v121
	v_cvt_pk_bf16_f32 v121, v122, v123
	v_mul_f32_e32 v124, v124, v188
	v_mul_f32_e32 v125, v125, v188
	v_mul_f32_e32 v126, v126, v188
	v_mul_f32_e32 v127, v127, v188
	v_cvt_pk_bf16_f32 v124, v124, v125
	v_cvt_pk_bf16_f32 v125, v126, v127
	ds_write2_b64 v184, v[120:121], v[124:125] offset0:32 offset1:36
	v_mul_f32_e32 v96, v96, v190
	v_mul_f32_e32 v97, v97, v190
	v_mul_f32_e32 v98, v98, v190
	v_mul_f32_e32 v99, v99, v190
	v_cvt_pk_bf16_f32 v96, v96, v97
	v_cvt_pk_bf16_f32 v97, v98, v99
	v_mul_f32_e32 v100, v100, v190
	v_mul_f32_e32 v101, v101, v190
	v_mul_f32_e32 v102, v102, v190
	v_mul_f32_e32 v103, v103, v190
	v_cvt_pk_bf16_f32 v100, v100, v101
	v_cvt_pk_bf16_f32 v101, v102, v103
	ds_write2_b64 v185, v[96:97], v[100:101] offset1:4
	v_mul_f32_e32 v112, v112, v190
	v_mul_f32_e32 v113, v113, v190
	v_mul_f32_e32 v114, v114, v190
	v_mul_f32_e32 v115, v115, v190
	v_cvt_pk_bf16_f32 v112, v112, v113
	v_cvt_pk_bf16_f32 v113, v114, v115
	v_mul_f32_e32 v116, v116, v190
	v_mul_f32_e32 v117, v117, v190
	v_mul_f32_e32 v118, v118, v190
	v_mul_f32_e32 v119, v119, v190
	v_cvt_pk_bf16_f32 v116, v116, v117
	v_cvt_pk_bf16_f32 v117, v118, v119
	ds_write2_b64 v185, v[112:113], v[116:117] offset0:32 offset1:36
	v_mul_f32_e32 v84, v84, v192
	v_mul_f32_e32 v85, v85, v192
	v_mul_f32_e32 v86, v86, v192
	v_mul_f32_e32 v87, v87, v192
	v_cvt_pk_bf16_f32 v84, v84, v85
	v_cvt_pk_bf16_f32 v85, v86, v87
	v_mul_f32_e32 v80, v80, v192
	v_mul_f32_e32 v81, v81, v192
	v_mul_f32_e32 v82, v82, v192
	v_mul_f32_e32 v83, v83, v192
	v_cvt_pk_bf16_f32 v80, v80, v81
	v_cvt_pk_bf16_f32 v81, v82, v83
	ds_write2_b64 v186, v[84:85], v[80:81] offset1:4
	v_mul_f32_e32 v92, v92, v192
	v_mul_f32_e32 v93, v93, v192
	v_mul_f32_e32 v94, v94, v192
	v_mul_f32_e32 v95, v95, v192
	v_cvt_pk_bf16_f32 v92, v92, v93
	v_cvt_pk_bf16_f32 v93, v94, v95
	v_mul_f32_e32 v88, v88, v192
	v_mul_f32_e32 v89, v89, v192
	v_mul_f32_e32 v90, v90, v192
	v_mul_f32_e32 v91, v91, v192
	v_cvt_pk_bf16_f32 v88, v88, v89
	v_cvt_pk_bf16_f32 v89, v90, v91
	ds_write2_b64 v186, v[92:93], v[88:89] offset0:32 offset1:36
	v_mul_f32_e32 v76, v76, v196
	v_mul_f32_e32 v77, v77, v196
	v_mul_f32_e32 v78, v78, v196
	v_mul_f32_e32 v79, v79, v196
	v_cvt_pk_bf16_f32 v76, v76, v77
	v_cvt_pk_bf16_f32 v77, v78, v79
	v_mul_f32_e32 v72, v72, v196
	v_mul_f32_e32 v73, v73, v196
	v_mul_f32_e32 v74, v74, v196
	v_mul_f32_e32 v75, v75, v196
	v_cvt_pk_bf16_f32 v72, v72, v73
	v_cvt_pk_bf16_f32 v73, v74, v75
	ds_write2_b64 v187, v[76:77], v[72:73] offset1:4
	v_mul_f32_e32 v68, v68, v196
	v_mul_f32_e32 v69, v69, v196
	v_mul_f32_e32 v70, v70, v196
	v_mul_f32_e32 v71, v71, v196
	v_cvt_pk_bf16_f32 v68, v68, v69
	v_cvt_pk_bf16_f32 v69, v70, v71
	v_mul_f32_e32 v64, v64, v196
	v_mul_f32_e32 v65, v65, v196
	v_mul_f32_e32 v66, v66, v196
	v_mul_f32_e32 v67, v67, v196
	v_cvt_pk_bf16_f32 v64, v64, v65
	v_cvt_pk_bf16_f32 v65, v66, v67
	ds_write2_b64 v187, v[68:69], v[64:65] offset0:32 offset1:36
;     ...
;     if (MODE == 0 || MODE == 3) {
;       char* ct = smem;
; #pragma unroll
;       for (int ai = 0; ai < 2; ++ai)
; #pragma unroll
;         for (int m = 0; m < 4; ++m) {
;           const int rloc = ai * HALF + wr * 64 + m * 16 + fr;
;           float rscale = 1.f;
;           if (MODE == 3) {
;             const long row = brow + rloc;
;             const float4 s0 = *(const float4*)(ssq + row * 8), s1 = *(const float4*)(ssq + row * 8 + 4);
;             rscale = rsqrtf((s0.x + s0.y + s0.z + s0.w + s1.x + s1.y + s1.z + s1.w) * (1.f / DM) + EPS);
;           }
; #pragma unroll
;           for (int bj = 0; bj < 2; ++bj)
; #pragma unroll
;             for (int n = 0; n < 2; ++n) {
;               const int cl = bj * HALF + wc * 32 + n * 16 + fq * 4;
;               f32x4 a = acc[ai][bj][m][n];
;               uint2 o;
;               o.x = pack2(a[0] * rscale, a[1] * rscale);
;               o.y = pack2(a[2] * rscale, a[3] * rscale);
;               *(uint2*)(ct + rloc * 528 + cl * 2) = o;
;             }
;         }
;       __syncthreads();
; #pragma unroll
;       for (int i = 0; i < 16; ++i) {
;         const int rloc = i * 16 + (tid_ >> 5), ch = tid_ & 31;
;         uint4 v = *(const uint4*)(ct + rloc * 528 + ch * 16);
;         typedef unsigned u32x4_t __attribute__((ext_vector_type(4)));
;         u32x4_t vv = {v.x, v.y, v.z, v.w};
;         __builtin_nontemporal_store(vv, (u32x4_t*)(Cb + (long)(brow + rloc) * ldc + bcol + ch * 8));
;       }
.Lp6_q0r:
	s_waitcnt lgkmcnt(0)
	s_barrier
	ds_read_b128 v[222:225], v177
	ds_read_b128 v[226:229], v177 offset:8448
	ds_read_b128 v[230:233], v177 offset:16896
	ds_read_b128 v[234:237], v177 offset:25344
	v_lshl_add_u64 v[238:239], v[182:183], 0, s[72:73]
	v_lshl_add_u64 v[240:241], v[238:239], 0, s[72:73]
	v_lshl_add_u64 v[242:243], v[240:241], 0, s[72:73]
	v_lshl_add_u64 v[244:245], v[242:243], 0, s[72:73]
	s_waitcnt lgkmcnt(3)
	global_store_dwordx4 v[182:183], v[222:225], off nt
	s_waitcnt lgkmcnt(2)
	global_store_dwordx4 v[238:239], v[226:229], off nt
	s_waitcnt lgkmcnt(1)
	global_store_dwordx4 v[240:241], v[230:233], off nt
	s_waitcnt lgkmcnt(0)
	global_store_dwordx4 v[242:243], v[234:237], off nt
	s_nop 1
	v_mov_b64_e32 v[182:183], v[244:245]
	s_barrier
	s_cmp_lg_u32 s62, 1
	s_cbranch_scc1 .Lp6_q1r
	ds_read_b64 v[188:189], v179 offset:512
	ds_read_b64 v[190:191], v179 offset:640
	ds_read_b64 v[192:193], v179 offset:768
	ds_read_b64 v[196:197], v179 offset:896
	s_waitcnt lgkmcnt(0)
	v_add_f32_e32 v188, v188, v189
	v_mul_f32_e32 v188, 0x3a000000, v188
	v_add_f32_e32 v188, 0x358637bd, v188
	v_rsq_f32_e32 v188, v188
	v_add_f32_e32 v190, v190, v191
	v_mul_f32_e32 v190, 0x3a000000, v190
	v_add_f32_e32 v190, 0x358637bd, v190
	v_rsq_f32_e32 v190, v190
	v_add_f32_e32 v192, v192, v193
	v_mul_f32_e32 v192, 0x3a000000, v192
	v_add_f32_e32 v192, 0x358637bd, v192
	v_rsq_f32_e32 v192, v192
	v_add_f32_e32 v196, v196, v197
	v_mul_f32_e32 v196, 0x3a000000, v196
	v_add_f32_e32 v196, 0x358637bd, v196
	v_rsq_f32_e32 v196, v196
	s_nop 0
	v_mul_f32_e32 v104, v104, v188
	v_mul_f32_e32 v105, v105, v188
	v_mul_f32_e32 v106, v106, v188
	v_mul_f32_e32 v107, v107, v188
	v_cvt_pk_bf16_f32 v104, v104, v105
	v_cvt_pk_bf16_f32 v105, v106, v107
	v_mul_f32_e32 v108, v108, v188
	v_mul_f32_e32 v109, v109, v188
	v_mul_f32_e32 v110, v110, v188
	v_mul_f32_e32 v111, v111, v188
	v_cvt_pk_bf16_f32 v108, v108, v109
	v_cvt_pk_bf16_f32 v109, v110, v111
	ds_write2_b64 v184, v[104:105], v[108:109] offset1:4
	v_mul_f32_e32 v120, v120, v188
	v_mul_f32_e32 v121, v121, v188
	v_mul_f32_e32 v122, v122, v188
	v_mul_f32_e32 v123, v123, v188
	v_cvt_pk_bf16_f32 v120, v120, v121
	v_cvt_pk_bf16_f32 v121, v122, v123
	v_mul_f32_e32 v124, v124, v188
	v_mul_f32_e32 v125, v125, v188
	v_mul_f32_e32 v126, v126, v188
	v_mul_f32_e32 v127, v127, v188
	v_cvt_pk_bf16_f32 v124, v124, v125
	v_cvt_pk_bf16_f32 v125, v126, v127
	ds_write2_b64 v184, v[120:121], v[124:125] offset0:32 offset1:36
	v_mul_f32_e32 v96, v96, v190
	v_mul_f32_e32 v97, v97, v190
	v_mul_f32_e32 v98, v98, v190
	v_mul_f32_e32 v99, v99, v190
	v_cvt_pk_bf16_f32 v96, v96, v97
	v_cvt_pk_bf16_f32 v97, v98, v99
	v_mul_f32_e32 v100, v100, v190
	v_mul_f32_e32 v101, v101, v190
	v_mul_f32_e32 v102, v102, v190
	v_mul_f32_e32 v103, v103, v190
	v_cvt_pk_bf16_f32 v100, v100, v101
	v_cvt_pk_bf16_f32 v101, v102, v103
	ds_write2_b64 v185, v[96:97], v[100:101] offset1:4
	v_mul_f32_e32 v112, v112, v190
	v_mul_f32_e32 v113, v113, v190
	v_mul_f32_e32 v114, v114, v190
	v_mul_f32_e32 v115, v115, v190
	v_cvt_pk_bf16_f32 v112, v112, v113
	v_cvt_pk_bf16_f32 v113, v114, v115
	v_mul_f32_e32 v116, v116, v190
	v_mul_f32_e32 v117, v117, v190
	v_mul_f32_e32 v118, v118, v190
	v_mul_f32_e32 v119, v119, v190
	v_cvt_pk_bf16_f32 v116, v116, v117
	v_cvt_pk_bf16_f32 v117, v118, v119
	ds_write2_b64 v185, v[112:113], v[116:117] offset0:32 offset1:36
	v_mul_f32_e32 v84, v84, v192
	v_mul_f32_e32 v85, v85, v192
	v_mul_f32_e32 v86, v86, v192
	v_mul_f32_e32 v87, v87, v192
	v_cvt_pk_bf16_f32 v84, v84, v85
	v_cvt_pk_bf16_f32 v85, v86, v87
	v_mul_f32_e32 v80, v80, v192
	v_mul_f32_e32 v81, v81, v192
	v_mul_f32_e32 v82, v82, v192
	v_mul_f32_e32 v83, v83, v192
	v_cvt_pk_bf16_f32 v80, v80, v81
	v_cvt_pk_bf16_f32 v81, v82, v83
	ds_write2_b64 v186, v[84:85], v[80:81] offset1:4
	v_mul_f32_e32 v92, v92, v192
	v_mul_f32_e32 v93, v93, v192
	v_mul_f32_e32 v94, v94, v192
	v_mul_f32_e32 v95, v95, v192
	v_cvt_pk_bf16_f32 v92, v92, v93
	v_cvt_pk_bf16_f32 v93, v94, v95
	v_mul_f32_e32 v88, v88, v192
	v_mul_f32_e32 v89, v89, v192
	v_mul_f32_e32 v90, v90, v192
	v_mul_f32_e32 v91, v91, v192
	v_cvt_pk_bf16_f32 v88, v88, v89
	v_cvt_pk_bf16_f32 v89, v90, v91
	ds_write2_b64 v186, v[92:93], v[88:89] offset0:32 offset1:36
	v_mul_f32_e32 v76, v76, v196
	v_mul_f32_e32 v77, v77, v196
	v_mul_f32_e32 v78, v78, v196
	v_mul_f32_e32 v79, v79, v196
	v_cvt_pk_bf16_f32 v76, v76, v77
	v_cvt_pk_bf16_f32 v77, v78, v79
	v_mul_f32_e32 v72, v72, v196
	v_mul_f32_e32 v73, v73, v196
	v_mul_f32_e32 v74, v74, v196
	v_mul_f32_e32 v75, v75, v196
	v_cvt_pk_bf16_f32 v72, v72, v73
	v_cvt_pk_bf16_f32 v73, v74, v75
	ds_write2_b64 v187, v[76:77], v[72:73] offset1:4
	v_mul_f32_e32 v68, v68, v196
	v_mul_f32_e32 v69, v69, v196
	v_mul_f32_e32 v70, v70, v196
	v_mul_f32_e32 v71, v71, v196
	v_cvt_pk_bf16_f32 v68, v68, v69
	v_cvt_pk_bf16_f32 v69, v70, v71
	v_mul_f32_e32 v64, v64, v196
	v_mul_f32_e32 v65, v65, v196
	v_mul_f32_e32 v66, v66, v196
	v_mul_f32_e32 v67, v67, v196
	v_cvt_pk_bf16_f32 v64, v64, v65
	v_cvt_pk_bf16_f32 v65, v66, v67
	ds_write2_b64 v187, v[68:69], v[64:65] offset0:32 offset1:36
;     ...
;     if (MODE == 0 || MODE == 3) {
;       char* ct = smem;
; #pragma unroll
;       for (int ai = 0; ai < 2; ++ai)
; #pragma unroll
;         for (int m = 0; m < 4; ++m) {
;           const int rloc = ai * HALF + wr * 64 + m * 16 + fr;
;           float rscale = 1.f;
;           if (MODE == 3) {
;             const long row = brow + rloc;
;             const float4 s0 = *(const float4*)(ssq + row * 8), s1 = *(const float4*)(ssq + row * 8 + 4);
;             rscale = rsqrtf((s0.x + s0.y + s0.z + s0.w + s1.x + s1.y + s1.z + s1.w) * (1.f / DM) + EPS);
;           }
; #pragma unroll
;           for (int bj = 0; bj < 2; ++bj)
; #pragma unroll
;             for (int n = 0; n < 2; ++n) {
;               const int cl = bj * HALF + wc * 32 + n * 16 + fq * 4;
;               f32x4 a = acc[ai][bj][m][n];
;               uint2 o;
;               o.x = pack2(a[0] * rscale, a[1] * rscale);
;               o.y = pack2(a[2] * rscale, a[3] * rscale);
;               *(uint2*)(ct + rloc * 528 + cl * 2) = o;
;             }
;         }
;       __syncthreads();
; #pragma unroll
;       for (int i = 0; i < 16; ++i) {
;         const int rloc = i * 16 + (tid_ >> 5), ch = tid_ & 31;
;         uint4 v = *(const uint4*)(ct + rloc * 528 + ch * 16);
;         typedef unsigned u32x4_t __attribute__((ext_vector_type(4)));
;         u32x4_t vv = {v.x, v.y, v.z, v.w};
;         __builtin_nontemporal_store(vv, (u32x4_t*)(Cb + (long)(brow + rloc) * ldc + bcol + ch * 8));
;       }
.Lp6_q1r:
	s_waitcnt lgkmcnt(0)
	s_barrier
	ds_read_b128 v[222:225], v177
	ds_read_b128 v[226:229], v177 offset:8448
	ds_read_b128 v[230:233], v177 offset:16896
	ds_read_b128 v[234:237], v177 offset:25344
	v_lshl_add_u64 v[238:239], v[182:183], 0, s[72:73]
	v_lshl_add_u64 v[240:241], v[238:239], 0, s[72:73]
	v_lshl_add_u64 v[242:243], v[240:241], 0, s[72:73]
	v_lshl_add_u64 v[244:245], v[242:243], 0, s[72:73]
	s_waitcnt lgkmcnt(3)
	global_store_dwordx4 v[182:183], v[222:225], off nt
	s_waitcnt lgkmcnt(2)
	global_store_dwordx4 v[238:239], v[226:229], off nt
	s_waitcnt lgkmcnt(1)
	global_store_dwordx4 v[240:241], v[230:233], off nt
	s_waitcnt lgkmcnt(0)
	global_store_dwordx4 v[242:243], v[234:237], off nt
	s_nop 1
	v_mov_b64_e32 v[182:183], v[244:245]
	s_barrier
	s_cmp_lg_u32 s62, 0
	s_cbranch_scc1 .Lp6_q2r
	ds_read_b64 v[188:189], v179 offset:1024
	ds_read_b64 v[190:191], v179 offset:1152
	ds_read_b64 v[192:193], v179 offset:1280
	ds_read_b64 v[196:197], v179 offset:1408
	s_waitcnt lgkmcnt(0)
	v_add_f32_e32 v188, v188, v189
	v_mul_f32_e32 v188, 0x3a000000, v188
	v_add_f32_e32 v188, 0x358637bd, v188
	v_rsq_f32_e32 v188, v188
	v_add_f32_e32 v190, v190, v191
	v_mul_f32_e32 v190, 0x3a000000, v190
	v_add_f32_e32 v190, 0x358637bd, v190
	v_rsq_f32_e32 v190, v190
	v_add_f32_e32 v192, v192, v193
	v_mul_f32_e32 v192, 0x3a000000, v192
	v_add_f32_e32 v192, 0x358637bd, v192
	v_rsq_f32_e32 v192, v192
	v_add_f32_e32 v196, v196, v197
	v_mul_f32_e32 v196, 0x3a000000, v196
	v_add_f32_e32 v196, 0x358637bd, v196
	v_rsq_f32_e32 v196, v196
	s_nop 0
	v_mul_f32_e32 v52, v52, v188
	v_mul_f32_e32 v53, v53, v188
	v_mul_f32_e32 v54, v54, v188
	v_mul_f32_e32 v55, v55, v188
	v_cvt_pk_bf16_f32 v52, v52, v53
	v_cvt_pk_bf16_f32 v53, v54, v55
	v_mul_f32_e32 v48, v48, v188
	v_mul_f32_e32 v49, v49, v188
	v_mul_f32_e32 v50, v50, v188
	v_mul_f32_e32 v51, v51, v188
	v_cvt_pk_bf16_f32 v48, v48, v49
	v_cvt_pk_bf16_f32 v49, v50, v51
	ds_write2_b64 v184, v[52:53], v[48:49] offset1:4
	v_mul_f32_e32 v60, v60, v188
	v_mul_f32_e32 v61, v61, v188
	v_mul_f32_e32 v62, v62, v188
	v_mul_f32_e32 v63, v63, v188
	v_cvt_pk_bf16_f32 v60, v60, v61
	v_cvt_pk_bf16_f32 v61, v62, v63
	v_mul_f32_e32 v56, v56, v188
	v_mul_f32_e32 v57, v57, v188
	v_mul_f32_e32 v58, v58, v188
	v_mul_f32_e32 v59, v59, v188
	v_cvt_pk_bf16_f32 v56, v56, v57
	v_cvt_pk_bf16_f32 v57, v58, v59
	ds_write2_b64 v184, v[60:61], v[56:57] offset0:32 offset1:36
	v_mul_f32_e32 v36, v36, v190
	v_mul_f32_e32 v37, v37, v190
	v_mul_f32_e32 v38, v38, v190
	v_mul_f32_e32 v39, v39, v190
	v_cvt_pk_bf16_f32 v36, v36, v37
	v_cvt_pk_bf16_f32 v37, v38, v39
	v_mul_f32_e32 v32, v32, v190
	v_mul_f32_e32 v33, v33, v190
	v_mul_f32_e32 v34, v34, v190
	v_mul_f32_e32 v35, v35, v190
	v_cvt_pk_bf16_f32 v32, v32, v33
	v_cvt_pk_bf16_f32 v33, v34, v35
	ds_write2_b64 v185, v[36:37], v[32:33] offset1:4
	v_mul_f32_e32 v44, v44, v190
	v_mul_f32_e32 v45, v45, v190
	v_mul_f32_e32 v46, v46, v190
	v_mul_f32_e32 v47, v47, v190
	v_cvt_pk_bf16_f32 v44, v44, v45
	v_cvt_pk_bf16_f32 v45, v46, v47
	v_mul_f32_e32 v40, v40, v190
	v_mul_f32_e32 v41, v41, v190
	v_mul_f32_e32 v42, v42, v190
	v_mul_f32_e32 v43, v43, v190
	v_cvt_pk_bf16_f32 v40, v40, v41
	v_cvt_pk_bf16_f32 v41, v42, v43
	ds_write2_b64 v185, v[44:45], v[40:41] offset0:32 offset1:36
	v_mul_f32_e32 v20, v20, v192
	v_mul_f32_e32 v21, v21, v192
	v_mul_f32_e32 v22, v22, v192
	v_mul_f32_e32 v23, v23, v192
	v_cvt_pk_bf16_f32 v20, v20, v21
	v_cvt_pk_bf16_f32 v21, v22, v23
	v_mul_f32_e32 v16, v16, v192
	v_mul_f32_e32 v17, v17, v192
	v_mul_f32_e32 v18, v18, v192
	v_mul_f32_e32 v19, v19, v192
	v_cvt_pk_bf16_f32 v16, v16, v17
	v_cvt_pk_bf16_f32 v17, v18, v19
	ds_write2_b64 v186, v[20:21], v[16:17] offset1:4
	v_mul_f32_e32 v28, v28, v192
	v_mul_f32_e32 v29, v29, v192
	v_mul_f32_e32 v30, v30, v192
	v_mul_f32_e32 v31, v31, v192
	v_cvt_pk_bf16_f32 v28, v28, v29
	v_cvt_pk_bf16_f32 v29, v30, v31
	v_mul_f32_e32 v24, v24, v192
	v_mul_f32_e32 v25, v25, v192
	v_mul_f32_e32 v26, v26, v192
	v_mul_f32_e32 v27, v27, v192
	v_cvt_pk_bf16_f32 v24, v24, v25
	v_cvt_pk_bf16_f32 v25, v26, v27
	ds_write2_b64 v186, v[28:29], v[24:25] offset0:32 offset1:36
	v_mul_f32_e32 v8, v8, v196
	v_mul_f32_e32 v9, v9, v196
	v_mul_f32_e32 v10, v10, v196
	v_mul_f32_e32 v11, v11, v196
	v_cvt_pk_bf16_f32 v8, v8, v9
	v_cvt_pk_bf16_f32 v9, v10, v11
	v_mul_f32_e32 v0, v0, v196
	v_mul_f32_e32 v1, v1, v196
	v_mul_f32_e32 v2, v2, v196
	v_mul_f32_e32 v3, v3, v196
	v_cvt_pk_bf16_f32 v0, v0, v1
	v_cvt_pk_bf16_f32 v1, v2, v3
	ds_write2_b64 v187, v[8:9], v[0:1] offset1:4
	v_mul_f32_e32 v12, v12, v196
	v_mul_f32_e32 v13, v13, v196
	v_mul_f32_e32 v14, v14, v196
	v_mul_f32_e32 v15, v15, v196
	v_cvt_pk_bf16_f32 v12, v12, v13
	v_cvt_pk_bf16_f32 v13, v14, v15
	v_mul_f32_e32 v4, v4, v196
	v_mul_f32_e32 v5, v5, v196
	v_mul_f32_e32 v6, v6, v196
	v_mul_f32_e32 v7, v7, v196
	v_cvt_pk_bf16_f32 v4, v4, v5
	v_cvt_pk_bf16_f32 v5, v6, v7
	ds_write2_b64 v187, v[12:13], v[4:5] offset0:32 offset1:36
;     ...
;     if (MODE == 0 || MODE == 3) {
;       char* ct = smem;
; #pragma unroll
;       for (int ai = 0; ai < 2; ++ai)
; #pragma unroll
;         for (int m = 0; m < 4; ++m) {
;           const int rloc = ai * HALF + wr * 64 + m * 16 + fr;
;           float rscale = 1.f;
;           if (MODE == 3) {
;             const long row = brow + rloc;
;             const float4 s0 = *(const float4*)(ssq + row * 8), s1 = *(const float4*)(ssq + row * 8 + 4);
;             rscale = rsqrtf((s0.x + s0.y + s0.z + s0.w + s1.x + s1.y + s1.z + s1.w) * (1.f / DM) + EPS);
;           }
; #pragma unroll
;           for (int bj = 0; bj < 2; ++bj)
; #pragma unroll
;             for (int n = 0; n < 2; ++n) {
;               const int cl = bj * HALF + wc * 32 + n * 16 + fq * 4;
;               f32x4 a = acc[ai][bj][m][n];
;               uint2 o;
;               o.x = pack2(a[0] * rscale, a[1] * rscale);
;               o.y = pack2(a[2] * rscale, a[3] * rscale);
;               *(uint2*)(ct + rloc * 528 + cl * 2) = o;
;             }
;         }
;       __syncthreads();
; #pragma unroll
;       for (int i = 0; i < 16; ++i) {
;         const int rloc = i * 16 + (tid_ >> 5), ch = tid_ & 31;
;         uint4 v = *(const uint4*)(ct + rloc * 528 + ch * 16);
;         typedef unsigned u32x4_t __attribute__((ext_vector_type(4)));
;         u32x4_t vv = {v.x, v.y, v.z, v.w};
;         __builtin_nontemporal_store(vv, (u32x4_t*)(Cb + (long)(brow + rloc) * ldc + bcol + ch * 8));
;       }
.Lp6_q2r:
	s_waitcnt lgkmcnt(0)
	s_barrier
	ds_read_b128 v[222:225], v177
	ds_read_b128 v[226:229], v177 offset:8448
	ds_read_b128 v[230:233], v177 offset:16896
	ds_read_b128 v[234:237], v177 offset:25344
	v_lshl_add_u64 v[238:239], v[182:183], 0, s[72:73]
	v_lshl_add_u64 v[240:241], v[238:239], 0, s[72:73]
	v_lshl_add_u64 v[242:243], v[240:241], 0, s[72:73]
	v_lshl_add_u64 v[244:245], v[242:243], 0, s[72:73]
	s_waitcnt lgkmcnt(3)
	global_store_dwordx4 v[182:183], v[222:225], off nt
	s_waitcnt lgkmcnt(2)
	global_store_dwordx4 v[238:239], v[226:229], off nt
	s_waitcnt lgkmcnt(1)
	global_store_dwordx4 v[240:241], v[230:233], off nt
	s_waitcnt lgkmcnt(0)
	global_store_dwordx4 v[242:243], v[234:237], off nt
	s_nop 1
	v_mov_b64_e32 v[182:183], v[244:245]
	s_barrier
	s_cmp_lg_u32 s62, 1
	s_cbranch_scc1 .Lp6_q3r
	ds_read_b64 v[188:189], v179 offset:1536
	ds_read_b64 v[190:191], v179 offset:1664
	ds_read_b64 v[192:193], v179 offset:1792
	ds_read_b64 v[196:197], v179 offset:1920
	s_waitcnt lgkmcnt(0)
	v_add_f32_e32 v188, v188, v189
	v_mul_f32_e32 v188, 0x3a000000, v188
	v_add_f32_e32 v188, 0x358637bd, v188
	v_rsq_f32_e32 v188, v188
	v_add_f32_e32 v190, v190, v191
	v_mul_f32_e32 v190, 0x3a000000, v190
	v_add_f32_e32 v190, 0x358637bd, v190
	v_rsq_f32_e32 v190, v190
	v_add_f32_e32 v192, v192, v193
	v_mul_f32_e32 v192, 0x3a000000, v192
	v_add_f32_e32 v192, 0x358637bd, v192
	v_rsq_f32_e32 v192, v192
	v_add_f32_e32 v196, v196, v197
	v_mul_f32_e32 v196, 0x3a000000, v196
	v_add_f32_e32 v196, 0x358637bd, v196
	v_rsq_f32_e32 v196, v196
	s_nop 0
	v_mul_f32_e32 v52, v52, v188
	v_mul_f32_e32 v53, v53, v188
	v_mul_f32_e32 v54, v54, v188
	v_mul_f32_e32 v55, v55, v188
	v_cvt_pk_bf16_f32 v52, v52, v53
	v_cvt_pk_bf16_f32 v53, v54, v55
	v_mul_f32_e32 v48, v48, v188
	v_mul_f32_e32 v49, v49, v188
	v_mul_f32_e32 v50, v50, v188
	v_mul_f32_e32 v51, v51, v188
	v_cvt_pk_bf16_f32 v48, v48, v49
	v_cvt_pk_bf16_f32 v49, v50, v51
	ds_write2_b64 v184, v[52:53], v[48:49] offset1:4
	v_mul_f32_e32 v60, v60, v188
	v_mul_f32_e32 v61, v61, v188
	v_mul_f32_e32 v62, v62, v188
	v_mul_f32_e32 v63, v63, v188
	v_cvt_pk_bf16_f32 v60, v60, v61
	v_cvt_pk_bf16_f32 v61, v62, v63
	v_mul_f32_e32 v56, v56, v188
	v_mul_f32_e32 v57, v57, v188
	v_mul_f32_e32 v58, v58, v188
	v_mul_f32_e32 v59, v59, v188
	v_cvt_pk_bf16_f32 v56, v56, v57
	v_cvt_pk_bf16_f32 v57, v58, v59
	ds_write2_b64 v184, v[60:61], v[56:57] offset0:32 offset1:36
	v_mul_f32_e32 v36, v36, v190
	v_mul_f32_e32 v37, v37, v190
	v_mul_f32_e32 v38, v38, v190
	v_mul_f32_e32 v39, v39, v190
	v_cvt_pk_bf16_f32 v36, v36, v37
	v_cvt_pk_bf16_f32 v37, v38, v39
	v_mul_f32_e32 v32, v32, v190
	v_mul_f32_e32 v33, v33, v190
	v_mul_f32_e32 v34, v34, v190
	v_mul_f32_e32 v35, v35, v190
	v_cvt_pk_bf16_f32 v32, v32, v33
	v_cvt_pk_bf16_f32 v33, v34, v35
	ds_write2_b64 v185, v[36:37], v[32:33] offset1:4
	v_mul_f32_e32 v44, v44, v190
	v_mul_f32_e32 v45, v45, v190
	v_mul_f32_e32 v46, v46, v190
	v_mul_f32_e32 v47, v47, v190
	v_cvt_pk_bf16_f32 v44, v44, v45
	v_cvt_pk_bf16_f32 v45, v46, v47
	v_mul_f32_e32 v40, v40, v190
	v_mul_f32_e32 v41, v41, v190
	v_mul_f32_e32 v42, v42, v190
	v_mul_f32_e32 v43, v43, v190
	v_cvt_pk_bf16_f32 v40, v40, v41
	v_cvt_pk_bf16_f32 v41, v42, v43
	ds_write2_b64 v185, v[44:45], v[40:41] offset0:32 offset1:36
	v_mul_f32_e32 v20, v20, v192
	v_mul_f32_e32 v21, v21, v192
	v_mul_f32_e32 v22, v22, v192
	v_mul_f32_e32 v23, v23, v192
	v_cvt_pk_bf16_f32 v20, v20, v21
	v_cvt_pk_bf16_f32 v21, v22, v23
	v_mul_f32_e32 v16, v16, v192
	v_mul_f32_e32 v17, v17, v192
	v_mul_f32_e32 v18, v18, v192
	v_mul_f32_e32 v19, v19, v192
	v_cvt_pk_bf16_f32 v16, v16, v17
	v_cvt_pk_bf16_f32 v17, v18, v19
	ds_write2_b64 v186, v[20:21], v[16:17] offset1:4
	v_mul_f32_e32 v28, v28, v192
	v_mul_f32_e32 v29, v29, v192
	v_mul_f32_e32 v30, v30, v192
	v_mul_f32_e32 v31, v31, v192
	v_cvt_pk_bf16_f32 v28, v28, v29
	v_cvt_pk_bf16_f32 v29, v30, v31
	v_mul_f32_e32 v24, v24, v192
	v_mul_f32_e32 v25, v25, v192
	v_mul_f32_e32 v26, v26, v192
	v_mul_f32_e32 v27, v27, v192
	v_cvt_pk_bf16_f32 v24, v24, v25
	v_cvt_pk_bf16_f32 v25, v26, v27
	ds_write2_b64 v186, v[28:29], v[24:25] offset0:32 offset1:36
	v_mul_f32_e32 v8, v8, v196
	v_mul_f32_e32 v9, v9, v196
	v_mul_f32_e32 v10, v10, v196
	v_mul_f32_e32 v11, v11, v196
	v_cvt_pk_bf16_f32 v8, v8, v9
	v_cvt_pk_bf16_f32 v9, v10, v11
	v_mul_f32_e32 v0, v0, v196
	v_mul_f32_e32 v1, v1, v196
	v_mul_f32_e32 v2, v2, v196
	v_mul_f32_e32 v3, v3, v196
	v_cvt_pk_bf16_f32 v0, v0, v1
	v_cvt_pk_bf16_f32 v1, v2, v3
	ds_write2_b64 v187, v[8:9], v[0:1] offset1:4
	v_mul_f32_e32 v12, v12, v196
	v_mul_f32_e32 v13, v13, v196
	v_mul_f32_e32 v14, v14, v196
	v_mul_f32_e32 v15, v15, v196
	v_cvt_pk_bf16_f32 v12, v12, v13
	v_cvt_pk_bf16_f32 v13, v14, v15
	v_mul_f32_e32 v4, v4, v196
	v_mul_f32_e32 v5, v5, v196
	v_mul_f32_e32 v6, v6, v196
	v_mul_f32_e32 v7, v7, v196
	v_cvt_pk_bf16_f32 v4, v4, v5
	v_cvt_pk_bf16_f32 v5, v6, v7
	ds_write2_b64 v187, v[12:13], v[4:5] offset0:32 offset1:36
.Lp6_q3r:
	s_waitcnt lgkmcnt(0)
	s_barrier
	ds_read_b128 v[222:225], v177
	ds_read_b128 v[226:229], v177 offset:8448
	ds_read_b128 v[230:233], v177 offset:16896
	ds_read_b128 v[234:237], v177 offset:25344
	v_lshl_add_u64 v[238:239], v[182:183], 0, s[72:73]
	v_lshl_add_u64 v[240:241], v[238:239], 0, s[72:73]
	v_lshl_add_u64 v[242:243], v[240:241], 0, s[72:73]
	v_lshl_add_u64 v[244:245], v[242:243], 0, s[72:73]
	s_waitcnt lgkmcnt(3)
	global_store_dwordx4 v[182:183], v[222:225], off nt
	s_waitcnt lgkmcnt(2)
	global_store_dwordx4 v[238:239], v[226:229], off nt
	s_waitcnt lgkmcnt(1)
	global_store_dwordx4 v[240:241], v[230:233], off nt
	s_waitcnt lgkmcnt(0)
	global_store_dwordx4 v[242:243], v[234:237], off nt
	s_nop 1
	v_mov_b64_e32 v[182:183], v[244:245]
	s_barrier
	s_cmp_eq_u32 s32, 1
	s_cbranch_scc1 .Lp6_hdr2
	s_branch .Lp6_exit

;     ...
;   for (int vw = blockIdx.x; vw < nwg; vw += gridDim.x) {
;     int tid_ = threadIdx.x;
;     asm volatile("" : "+v"(tid_));
;     const int wid = tid_ >> 6, lane = tid_ & 63, wr = wid >> 2, wc = wid & 3, fr = lane & 15, fq = lane >> 4;
;     int brow, bcol;
;     TILE_COORDS(vw, brow, bcol);
;     f32x4 acc[2][2][4][2] = {};
;     bf16x8 At[4][2], B0[2][2], B1[2][2];
;     STAGE(SB(0, 0), Bt, bcol, 0); STAGE(SA(0, 0), A, brow, 0);
;     STAGE(SB(0, 1), Bt, bcol + HALF, 0); STAGE(SA(0, 1), A, brow + HALF, 0);
.LBB0_547:
	s_add_i32 s4, s23, s4
	v_ashrrev_i32_e32 v200, 31, v144
	s_ashr_i32 s5, s4, 31
	v_lshrrev_b32_e32 v200, 26, v200
	s_lshr_b32 s5, s5, 25
	v_add_u32_e32 v200, v144, v200
	s_add_i32 s26, s4, s5
	v_ashrrev_i32_e32 v201, 6, v200
	v_bfe_i32 v200, v144, 27, 1
	s_and_b32 s5, s26, 0xff80
	v_lshlrev_b32_e32 v151, 4, v144
	v_lshrrev_b32_e32 v200, 22, v200
	s_sub_i32 s4, s4, s5
	v_add_u32_e32 v200, v151, v200
	s_bfe_i32 s5, s4, 0x80000
	v_and_b32_e32 v200, 0xfffffc00, v200
	s_bfe_u32 s5, s5, 0x2000d
	v_sub_u32_e32 v200, v151, v200
	s_add_i32 s5, s4, s5
	v_lshrrev_b32_e32 v202, 4, v200
	s_bfe_i32 s22, s5, 0x80000
	s_and_b32 s5, s5, 0xfc
	v_bitop3_b32 v202, v202, v200, 32 bitop3:0x6c
	s_sub_i32 s4, s4, s5
	v_ashrrev_i32_e32 v203, 31, v202
	s_sext_i32_i16 s22, s22
	s_sext_i32_i8 s4, s4
	v_lshrrev_b32_e32 v203, 26, v203
	s_lshl_b32 s27, s4, 8
	s_lshl_b32 s4, s22, 6
	v_add_u32_e32 v203, v202, v203
	s_and_b32 s22, s4, 0xffffff00
	v_readlane_b32 s40, v248, 10
	v_lshlrev_b32_e32 v200, 3, v201
	v_ashrrev_i32_e32 v204, 6, v203
	v_and_b32_e32 v203, 0xc0, v203
	s_ashr_i32 s23, s22, 31
	v_readlane_b32 s42, v248, 12
	v_readlane_b32 s43, v248, 13
	v_and_b32_e32 v200, -16, v200
	v_lshlrev_b32_e32 v201, 5, v201
	v_sub_u32_e32 v202, v202, v203
	s_lshl_b64 s[4:5], s[22:23], 12
	s_mov_b64 s[38:39], s[42:43]
	v_add_u32_e32 v200, v204, v200
	v_and_b32_e32 v201, 32, v201
	v_ashrrev_i16_sdwa v202, v150, sext(v202) dst_sel:DWORD dst_unused:UNUSED_PAD src0_sel:DWORD src1_sel:BYTE_0
	s_add_u32 s24, s38, s4
	v_add_u32_sdwa v202, v201, sext(v202) dst_sel:DWORD dst_unused:UNUSED_PAD src0_sel:DWORD src1_sel:WORD_0
	v_ashrrev_i32_e32 v201, 31, v200
	s_addc_u32 s25, s39, s5
	v_lshlrev_b64 v[200:201], 12, v[200:201]
	v_ashrrev_i32_e32 v203, 31, v202
	v_lshl_add_u64 v[204:205], s[24:25], 0, v[200:201]
	v_lshlrev_b64 v[202:203], 1, v[202:203]
	v_add_u32_e32 v220, 0x2000, v151
	v_lshl_add_u64 v[208:209], v[204:205], 0, v[202:203]
	v_ashrrev_i32_e32 v204, 31, v220
	v_lshrrev_b32_e32 v204, 22, v204
	v_add_u32_e32 v204, v220, v204
	v_ashrrev_i32_e32 v205, 10, v204
	v_mul_i32_i24_e32 v204, 0x400, v205
	v_sub_u32_e32 v204, v220, v204
	v_lshrrev_b32_e32 v206, 4, v204
	v_bitop3_b32 v206, v206, v204, 32 bitop3:0x6c
	v_ashrrev_i32_e32 v207, 31, v206
	v_lshrrev_b32_e32 v207, 26, v207
	v_add_u32_e32 v207, v206, v207
	v_lshlrev_b32_e32 v204, 3, v205
	v_ashrrev_i32_e32 v210, 6, v207
	v_and_b32_e32 v207, 0xc0, v207
	v_and_b32_e32 v204, -16, v204
	v_lshlrev_b32_e32 v205, 5, v205
	v_sub_u32_e32 v206, v206, v207
	v_add_u32_e32 v204, v210, v204
	v_and_b32_e32 v205, 32, v205
	v_ashrrev_i16_sdwa v206, v150, sext(v206) dst_sel:DWORD dst_unused:UNUSED_PAD src0_sel:DWORD src1_sel:BYTE_0
	v_add_u32_e32 v140, s19, v151
	v_add_u32_sdwa v206, v205, sext(v206) dst_sel:DWORD dst_unused:UNUSED_PAD src0_sel:DWORD src1_sel:WORD_0
	v_ashrrev_i32_e32 v205, 31, v204
	v_readfirstlane_b32 s28, v140
	v_lshlrev_b64 v[204:205], 12, v[204:205]
	v_add_u32_e32 v212, s19, v220
	s_mov_b32 m0, s28
	v_lshl_add_u64 v[210:211], s[24:25], 0, v[204:205]
	v_readfirstlane_b32 s24, v212
	global_load_lds_dwordx4 v[208:209], off
	s_mov_b32 m0, s24
	s_lshl_b32 s24, s26, 3
	s_and_b32 s24, s24, 0xfffffc00
	s_add_i32 s24, s27, s24
	s_ashr_i32 s25, s24, 31
	s_lshl_b64 s[26:27], s[24:25], 12
	s_add_u32 s28, s90, s26
	s_addc_u32 s29, s91, s27
	v_lshl_add_u64 v[212:213], s[28:29], 0, v[200:201]
	v_lshl_add_u64 v[214:215], s[28:29], 0, v[204:205]
	s_or_b32 s28, s22, 0x80
	s_ashr_i32 s29, s28, 31
	s_lshl_b64 s[28:29], s[28:29], 12
	s_add_u32 s28, s38, s28
	v_ashrrev_i32_e32 v207, 31, v206
	s_addc_u32 s29, s39, s29
	v_lshlrev_b64 v[206:207], 1, v[206:207]
	v_add_u32_e32 v147, 0, v151
	v_lshl_add_u64 v[216:217], s[28:29], 0, v[200:201]
	v_lshl_add_u64 v[218:219], s[28:29], 0, v[204:205]
	s_or_b32 s28, s24, 0x80
	v_lshl_add_u64 v[210:211], v[210:211], 0, v[206:207]
	v_readfirstlane_b32 s25, v147
	v_add_u32_e32 v153, 0x2000, v147
	s_ashr_i32 s29, s28, 31
	global_load_lds_dwordx4 v[210:211], off
	v_lshl_add_u64 v[212:213], v[212:213], 0, v[202:203]
	s_mov_b32 m0, s25
	v_readfirstlane_b32 s25, v153
	v_add_u32_e32 v155, s21, v151
	s_lshl_b64 s[28:29], s[28:29], 12
	global_load_lds_dwordx4 v[212:213], off
	v_lshl_add_u64 v[214:215], v[214:215], 0, v[206:207]
	s_mov_b32 m0, s25
	v_readfirstlane_b32 s25, v155
	v_add_u32_e32 v220, s21, v220
	s_add_u32 s28, s90, s28
	global_load_lds_dwordx4 v[214:215], off
	v_lshl_add_u64 v[216:217], v[216:217], 0, v[202:203]
	s_mov_b32 m0, s25
	v_readfirstlane_b32 s25, v220
	s_addc_u32 s29, s91, s29
	v_add_u32_e32 v157, 0x4000, v147
	global_load_lds_dwordx4 v[216:217], off
	v_lshl_add_u64 v[218:219], v[218:219], 0, v[206:207]
	s_mov_b32 m0, s25
	v_lshl_add_u64 v[220:221], s[28:29], 0, v[200:201]
	v_readfirstlane_b32 s25, v157
	v_add_u32_e32 v158, 0x6000, v147
	global_load_lds_dwordx4 v[218:219], off
	v_lshl_add_u64 v[128:129], v[220:221], 0, v[202:203]
	s_mov_b32 m0, s25
	v_lshl_add_u64 v[220:221], s[28:29], 0, v[204:205]
	v_readfirstlane_b32 s25, v158
	global_load_lds_dwordx4 v[128:129], off
	v_lshl_add_u64 v[130:131], v[220:221], 0, v[206:207]
	s_mov_b32 m0, s25
	v_ashrrev_i32_e32 v220, 8, v144
	global_load_lds_dwordx4 v[130:131], off
	s_cmp_lg_u32 s32, 0
	s_cbranch_scc1 .Lp6_epi
; #define WAIT_V(n) asm volatile("s_waitcnt vmcnt(" #n ")" ::: "memory")
; #define BAR __builtin_amdgcn_s_barrier()
;     ...
;     f32x4 acc[2][2][4][2] = {};
;     bf16x8 At[4][2], B0[2][2], B1[2][2];
;     STAGE(SB(0, 0), Bt, bcol, 0); STAGE(SA(0, 0), A, brow, 0);
;     STAGE(SB(0, 1), Bt, bcol + HALF, 0); STAGE(SA(0, 1), A, brow + HALF, 0);
;     if (wr == 1) BAR;
;     WAIT_V(4); BAR;
;     STAGE(SB(1, 0), Bt, bcol, 1); STAGE(SA(1, 0), A, brow, 1); STAGE(SB(1, 1), Bt, bcol + HALF, 1);
.Lp6_hdr2:
	v_mov_b64_e32 v[22:23], 0
	v_mov_b64_e32 v[24:25], 0
	v_mov_b64_e32 v[26:27], 0
	v_mov_b64_e32 v[28:29], 0
	v_mov_b64_e32 v[30:31], 0
	v_mov_b64_e32 v[32:33], 0
	v_mov_b64_e32 v[34:35], 0
	v_mov_b64_e32 v[36:37], 0
	v_mov_b64_e32 v[38:39], 0
	v_mov_b64_e32 v[40:41], 0
	v_mov_b64_e32 v[42:43], 0
	v_mov_b64_e32 v[44:45], 0
	v_mov_b64_e32 v[46:47], 0
	v_mov_b64_e32 v[48:49], 0
	v_mov_b64_e32 v[50:51], 0
	v_mov_b64_e32 v[52:53], 0
	v_mov_b64_e32 v[54:55], 0
	v_mov_b64_e32 v[56:57], 0
	v_mov_b64_e32 v[58:59], 0
	v_mov_b64_e32 v[60:61], 0
	v_mov_b64_e32 v[62:63], 0
	v_mov_b64_e32 v[64:65], 0
	v_mov_b64_e32 v[66:67], 0
	v_mov_b64_e32 v[68:69], 0
	v_mov_b64_e32 v[70:71], 0
	v_mov_b64_e32 v[72:73], 0
	v_mov_b64_e32 v[74:75], 0
	v_mov_b64_e32 v[76:77], 0
	v_mov_b64_e32 v[78:79], 0
	v_mov_b64_e32 v[80:81], 0
	v_mov_b64_e32 v[82:83], 0
	v_mov_b64_e32 v[84:85], 0
	v_mov_b64_e32 v[86:87], 0
	v_mov_b64_e32 v[88:89], 0
	v_mov_b64_e32 v[90:91], 0
	v_mov_b64_e32 v[92:93], 0
	v_mov_b64_e32 v[94:95], 0
	v_mov_b64_e32 v[96:97], 0
	v_mov_b64_e32 v[98:99], 0
	v_mov_b64_e32 v[100:101], 0
	v_mov_b64_e32 v[102:103], 0
	v_mov_b64_e32 v[104:105], 0
	v_mov_b64_e32 v[106:107], 0
	v_mov_b64_e32 v[108:109], 0
	v_mov_b64_e32 v[110:111], 0
	v_mov_b64_e32 v[112:113], 0
	v_mov_b64_e32 v[114:115], 0
	v_mov_b64_e32 v[116:117], 0
	v_mov_b64_e32 v[118:119], 0
	v_mov_b64_e32 v[120:121], 0
	v_mov_b64_e32 v[122:123], 0
	v_mov_b64_e32 v[124:125], 0
	v_mov_b64_e32 v[126:127], 0
	v_cmp_eq_u32_e32 vcc, 1, v220
	v_readlane_b32 s41, v248, 11
	v_readlane_b32 s44, v248, 14
	v_readlane_b32 s45, v248, 15
	v_readlane_b32 s46, v248, 16
	v_readlane_b32 s47, v248, 17
	v_readlane_b32 s48, v248, 18
	v_readlane_b32 s49, v248, 19
	v_readlane_b32 s50, v248, 20
	v_readlane_b32 s51, v248, 21
	v_readlane_b32 s52, v248, 22
	v_readlane_b32 s53, v248, 23
	v_readlane_b32 s54, v248, 24
	v_readlane_b32 s55, v248, 25
	s_and_saveexec_b64 s[28:29], vcc
	s_cbranch_execz .LBB0_549
	s_barrier
.LBB0_549:
	s_or_b64 exec, exec, s[28:29]
	v_add_u32_e32 v159, s30, v151
	v_add_u32_e32 v160, 0x2000, v159
	v_readfirstlane_b32 s25, v159
	v_lshl_add_u64 v[208:209], v[208:209], 0, s[2:3]
	s_mov_b32 m0, s25
	v_readfirstlane_b32 s25, v160
	v_add_u32_e32 v161, 0x8000, v147
	s_cmp_eq_u32 s32, 0
	s_cbranch_scc1 .Lp6_w2a
	s_waitcnt vmcnt(18)
	s_branch .Lp6_w2b

; #define WAIT_V(n) asm volatile("s_waitcnt vmcnt(" #n ")" ::: "memory")
; #define BAR __builtin_amdgcn_s_barrier()
;     ...
;     STAGE(SB(1, 0), Bt, bcol, 1); STAGE(SA(1, 0), A, brow, 1); STAGE(SB(1, 1), Bt, bcol + HALF, 1);
;     WAIT_V(6); BAR;
.Lp6_w2b:
	s_barrier
	global_load_lds_dwordx4 v[208:209], off
	v_lshl_add_u64 v[208:209], v[210:211], 0, s[2:3]
	s_mov_b32 m0, s25
	v_readfirstlane_b32 s25, v161
	v_add_u32_e32 v162, 0xa000, v147
	global_load_lds_dwordx4 v[208:209], off
	v_lshl_add_u64 v[208:209], v[212:213], 0, s[2:3]
	s_mov_b32 m0, s25
	v_readfirstlane_b32 s25, v162
	v_add_u32_e32 v163, s31, v151
	global_load_lds_dwordx4 v[208:209], off
	v_lshl_add_u64 v[208:209], v[214:215], 0, s[2:3]
	s_mov_b32 m0, s25
	v_readfirstlane_b32 s25, v163
	v_add_u32_e32 v164, 0x2000, v163
	global_load_lds_dwordx4 v[208:209], off
	v_lshl_add_u64 v[208:209], v[216:217], 0, s[2:3]
	s_mov_b32 m0, s25
	v_readfirstlane_b32 s25, v164
	global_load_lds_dwordx4 v[208:209], off
	v_lshl_add_u64 v[208:209], v[218:219], 0, s[2:3]
	s_mov_b32 m0, s25
	v_and_b32_e32 v221, 15, v144
	global_load_lds_dwordx4 v[208:209], off
	v_bfe_u32 v149, v144, 4, 2
	v_lshlrev_b32_e32 v211, 2, v144
	v_lshlrev_b32_e32 v208, 4, v149
	v_lshlrev_b32_e32 v209, 6, v221
	v_and_b32_e32 v211, 32, v211
	v_bitop3_b32 v209, v208, v211, v209 bitop3:0x36
	v_add_u32_e32 v212, s19, v209
	v_add_u32_e32 v213, s21, v209
	v_add_u32_e32 v214, s30, v209
	v_add_u32_e32 v215, s31, v209
	v_add_u32_e32 v217, 0, v209
	v_lshlrev_b32_e32 v209, 6, v144
	v_and_or_b32 v208, v209, s33, v208
	v_xad_u32 v211, v208, v211, 0
	v_lshl_add_u64 v[208:209], s[4:5], 0, v[200:201]
	v_readlane_b32 s40, v248, 10
	v_lshl_add_u64 v[200:201], s[26:27], 0, v[200:201]
	v_readlane_b32 s42, v248, 12
	v_readlane_b32 s43, v248, 13
	v_lshl_add_u64 v[200:201], v[200:201], 0, v[202:203]
	v_lshl_add_u64 v[208:209], v[208:209], 0, v[202:203]
	s_mov_b64 s[38:39], s[42:43]
	v_lshl_add_u64 v[136:137], s[90:91], 0, v[200:201]
	v_lshl_add_u64 v[200:201], s[26:27], 0, v[204:205]
	v_bfe_u32 v148, v144, 6, 2
	s_cmp_eq_u32 s32, 0
	s_cbranch_scc1 .Lp6_w6a
	s_waitcnt vmcnt(22)
	s_branch .Lp6_w6b

; #define WAIT_V(n) asm volatile("s_waitcnt vmcnt(" #n ")" ::: "memory")
; #define WAIT_L(n) asm volatile("s_waitcnt lgkmcnt(" #n ")" ::: "memory")
; #define BAR __builtin_amdgcn_s_barrier()
; #define SCHED __builtin_amdgcn_sched_barrier(0)
;     ...
;     WAIT_V(6); BAR;
;     for (int t = 0; t < nt - 2; t += 2) {
;       LDB(B0, 0, 0); SCHED; LDA(At, 0, 0); STAGE(SA(1, 1), A, brow + HALF, t + 1);
;       WAIT_L(8); BAR; WAIT_L(0); MMA(0, 0, At, B0); BAR; SCHED;
;       LDB(B1, 0, 1); STAGE(SB(0, 0), Bt, bcol, t + 2);
;       BAR; WAIT_L(0); MMA(0, 1, At, B1); BAR;
;       LDA(At, 0, 1); STAGE(SA(0, 0), A, brow, t + 2);
;       BAR; WAIT_L(0); MMA(1, 0, At, B0); BAR; SCHED;
;       STAGE(SB(0, 1), Bt, bcol + HALF, t + 2);
;       WAIT_V(6); BAR; MMA(1, 1, At, B1); BAR;
.Lp6_w6b:
	v_lshlrev_b32_e32 v216, 13, v220
	v_lshl_add_u64 v[132:133], s[38:39], 0, v[208:209]
	v_lshl_add_u64 v[208:209], s[4:5], 0, v[204:205]
	v_lshl_add_u64 v[200:201], v[200:201], 0, v[206:207]
	v_lshlrev_b32_e32 v210, 12, v148
	v_lshl_or_b32 v152, v220, 6, v221
	v_or_b32_e32 v218, 0x800, v216
	v_or_b32_e32 v219, 0x1000, v216
	v_or_b32_e32 v220, 0x1800, v216
	v_lshl_add_u64 v[208:209], v[208:209], 0, v[206:207]
	v_lshl_add_u64 v[138:139], s[90:91], 0, v[200:201]
	v_mov_b32_e32 v0, 0
	v_lshl_add_u64 v[134:135], s[38:39], 0, v[208:209]
	s_mov_b32 s25, -2
	s_mov_b64 s[4:5], 0
	v_add_u32_e32 v166, v212, v210
	v_add_u32_e32 v146, v217, v216
	v_add_u32_e32 v143, v211, v218
	v_add_u32_e32 v142, v211, v219
	v_add_u32_e32 v141, v211, v220
	v_add_u32_e32 v165, v213, v210
	v_add_u32_e32 v156, v214, v210
	v_add_u32_e32 v154, v215, v210
	v_mov_b32_e32 v1, v0
	v_mov_b32_e32 v2, v0
	v_mov_b32_e32 v3, v0
	v_mov_b32_e32 v4, v0
	v_mov_b32_e32 v5, v0
	v_mov_b32_e32 v6, v0
	v_mov_b32_e32 v7, v0
	v_mov_b32_e32 v8, v0
	v_mov_b32_e32 v9, v0
	v_mov_b32_e32 v10, v0
	v_mov_b32_e32 v11, v0
	v_mov_b32_e32 v12, v0
	v_mov_b32_e32 v13, v0
	v_mov_b32_e32 v14, v0
	v_mov_b32_e32 v15, v0
	v_mov_b32_e32 v16, v0
	v_mov_b32_e32 v17, v0
	v_mov_b32_e32 v18, v0
	v_mov_b32_e32 v19, v0
	v_mov_b32_e32 v20, v0
	v_mov_b32_e32 v21, v0
	s_barrier
	v_readlane_b32 s41, v248, 11
	v_readlane_b32 s44, v248, 14
	v_readlane_b32 s45, v248, 15
	v_readlane_b32 s46, v248, 16
	v_readlane_b32 s47, v248, 17
	v_readlane_b32 s48, v248, 18
	v_readlane_b32 s49, v248, 19
	v_readlane_b32 s50, v248, 20
	v_readlane_b32 s51, v248, 21
	v_readlane_b32 s52, v248, 22
	v_readlane_b32 s53, v248, 23
	v_readlane_b32 s54, v248, 24
	v_readlane_b32 s55, v248, 25
.LBB0_550:
	v_add_u32_e32 v167, 0xc000, v147
	v_add_u32_e32 v168, 0xe000, v147
	v_add_u32_e32 v169, 0x2000, v140
	v_add_u32_e32 v169, 0x2000, v155
	ds_read_b128 v[170:173], v166
	ds_read_b128 v[174:177], v166 offset:1024
	ds_read_b128 v[178:181], v166 offset:2048
	ds_read_b128 v[182:185], v166 offset:3072
	ds_read_b128 v[186:189], v146
	ds_read_b128 v[190:193], v146 offset:1024
	ds_read_b128 v[196:199], v143
	ds_read_b128 v[200:203], v143 offset:1024
	ds_read_b128 v[204:207], v142
	ds_read_b128 v[208:211], v142 offset:1024
	ds_read_b128 v[212:215], v141
	ds_read_b128 v[216:219], v141 offset:1024
	ds_read_b128 v[220:223], v165
	ds_read_b128 v[224:227], v165 offset:1024
	ds_read_b128 v[228:231], v165 offset:2048
	ds_read_b128 v[232:235], v165 offset:3072
	v_add_u32_e32 v254, 0xc000, v147
	v_lshl_add_u64 v[250:251], v[136:137], 0, s[4:5]
	v_readfirstlane_b32 s26, v254
	v_lshl_add_u64 v[250:251], v[250:251], 0, s[6:7]
	s_mov_b32 m0, s26
	s_nop 0
	global_load_lds_dwordx4 v[250:251], off
	v_add_u32_e32 v254, 0xe000, v147
	v_lshl_add_u64 v[252:253], v[138:139], 0, s[4:5]
	v_readfirstlane_b32 s26, v254
	v_lshl_add_u64 v[252:253], v[252:253], 0, s[6:7]
	s_mov_b32 m0, s26
	s_nop 0
	global_load_lds_dwordx4 v[252:253], off
	s_waitcnt lgkmcnt(0)
	s_barrier
	s_setprio 1
	v_mfma_f32_16x16x32_bf16 v[124:127], v[170:173], v[186:189], v[124:127]
	v_mfma_f32_16x16x32_bf16 v[120:123], v[178:181], v[186:189], v[120:123]
	v_mfma_f32_16x16x32_bf16 v[116:119], v[170:173], v[196:199], v[116:119]
	v_mfma_f32_16x16x32_bf16 v[112:115], v[178:181], v[196:199], v[112:115]
	v_mfma_f32_16x16x32_bf16 v[108:111], v[170:173], v[204:207], v[108:111]
	v_mfma_f32_16x16x32_bf16 v[104:107], v[178:181], v[204:207], v[104:107]
	v_mfma_f32_16x16x32_bf16 v[100:103], v[170:173], v[212:215], v[100:103]
	v_mfma_f32_16x16x32_bf16 v[96:99], v[178:181], v[212:215], v[96:99]
	v_mfma_f32_16x16x32_bf16 v[124:127], v[174:177], v[190:193], v[124:127]
	v_mfma_f32_16x16x32_bf16 v[120:123], v[182:185], v[190:193], v[120:123]
	v_mfma_f32_16x16x32_bf16 v[116:119], v[174:177], v[200:203], v[116:119]
	v_mfma_f32_16x16x32_bf16 v[112:115], v[182:185], v[200:203], v[112:115]
	v_mfma_f32_16x16x32_bf16 v[108:111], v[174:177], v[208:211], v[108:111]
	v_mfma_f32_16x16x32_bf16 v[104:107], v[182:185], v[208:211], v[104:107]
	v_mfma_f32_16x16x32_bf16 v[100:103], v[174:177], v[216:219], v[100:103]
	v_mfma_f32_16x16x32_bf16 v[96:99], v[182:185], v[216:219], v[96:99]
	v_mfma_f32_16x16x32_bf16 v[92:95], v[220:223], v[186:189], v[92:95]
	v_mfma_f32_16x16x32_bf16 v[88:91], v[228:231], v[186:189], v[88:91]
	v_mfma_f32_16x16x32_bf16 v[84:87], v[220:223], v[196:199], v[84:87]
	v_mfma_f32_16x16x32_bf16 v[80:83], v[228:231], v[196:199], v[80:83]
	v_mfma_f32_16x16x32_bf16 v[76:79], v[220:223], v[204:207], v[76:79]
	v_mfma_f32_16x16x32_bf16 v[72:75], v[228:231], v[204:207], v[72:75]
	v_mfma_f32_16x16x32_bf16 v[68:71], v[220:223], v[212:215], v[68:71]
	v_mfma_f32_16x16x32_bf16 v[64:67], v[228:231], v[212:215], v[64:67]
	v_mfma_f32_16x16x32_bf16 v[92:95], v[224:227], v[190:193], v[92:95]
	v_mfma_f32_16x16x32_bf16 v[88:91], v[232:235], v[190:193], v[88:91]
	v_mfma_f32_16x16x32_bf16 v[84:87], v[224:227], v[200:203], v[84:87]
	v_mfma_f32_16x16x32_bf16 v[80:83], v[232:235], v[200:203], v[80:83]
	v_mfma_f32_16x16x32_bf16 v[76:79], v[224:227], v[208:211], v[76:79]
	v_mfma_f32_16x16x32_bf16 v[72:75], v[232:235], v[208:211], v[72:75]
	v_mfma_f32_16x16x32_bf16 v[68:71], v[224:227], v[216:219], v[68:71]
	v_mfma_f32_16x16x32_bf16 v[64:67], v[232:235], v[216:219], v[64:67]
	s_setprio 0
	s_barrier
; #define WAIT_V(n) asm volatile("s_waitcnt vmcnt(" #n ")" ::: "memory")
; #define WAIT_L(n) asm volatile("s_waitcnt lgkmcnt(" #n ")" ::: "memory")
; #define BAR __builtin_amdgcn_s_barrier()
; #define SCHED __builtin_amdgcn_sched_barrier(0)
;     ...
;       LDB(B1, 0, 1); STAGE(SB(0, 0), Bt, bcol, t + 2);
;       BAR; WAIT_L(0); MMA(0, 1, At, B1); BAR;
;       LDA(At, 0, 1); STAGE(SA(0, 0), A, brow, t + 2);
;       BAR; WAIT_L(0); MMA(1, 0, At, B0); BAR; SCHED;
;       STAGE(SB(0, 1), Bt, bcol + HALF, t + 2);
;       WAIT_V(6); BAR; MMA(1, 1, At, B1); BAR;
;       LDB(B0, 1, 0); SCHED; LDA(At, 1, 0); STAGE(SA(0, 1), A, brow + HALF, t + 2);
;       WAIT_L(8); BAR; WAIT_L(0); MMA(0, 0, At, B0); BAR; SCHED;
	ds_read_b128 v[186:189], v146 offset:16384
	ds_read_b128 v[190:193], v146 offset:17408
	ds_read_b128 v[196:199], v143 offset:16384
	ds_read_b128 v[200:203], v143 offset:17408
	ds_read_b128 v[204:207], v142 offset:16384
	ds_read_b128 v[208:211], v142 offset:17408
	ds_read_b128 v[212:215], v141 offset:16384
	ds_read_b128 v[216:219], v141 offset:17408
	v_lshl_add_u64 v[250:251], v[132:133], 0, s[4:5]
	v_readfirstlane_b32 s26, v140
	v_lshl_add_u64 v[250:251], v[250:251], 0, s[8:9]
	s_mov_b32 m0, s26
	s_nop 0
	global_load_lds_dwordx4 v[250:251], off
	v_add_u32_e32 v254, 0x2000, v140
	v_lshl_add_u64 v[252:253], v[134:135], 0, s[4:5]
	v_readfirstlane_b32 s26, v254
	v_lshl_add_u64 v[252:253], v[252:253], 0, s[8:9]
	s_mov_b32 m0, s26
	s_nop 0
	global_load_lds_dwordx4 v[252:253], off
	v_lshl_add_u64 v[250:251], v[136:137], 0, s[4:5]
	v_readfirstlane_b32 s26, v147
	v_lshl_add_u64 v[250:251], v[250:251], 0, s[8:9]
	s_mov_b32 m0, s26
	s_nop 0
	global_load_lds_dwordx4 v[250:251], off
	v_lshl_add_u64 v[252:253], v[138:139], 0, s[4:5]
	v_readfirstlane_b32 s26, v153
	v_lshl_add_u64 v[252:253], v[252:253], 0, s[8:9]
	s_mov_b32 m0, s26
	s_nop 0
	global_load_lds_dwordx4 v[252:253], off
	v_lshl_add_u64 v[250:251], v[132:133], 0, s[4:5]
	v_readfirstlane_b32 s26, v155
	v_lshl_add_u64 v[250:251], v[250:251], 0, s[10:11]
	s_mov_b32 m0, s26
	s_nop 0
	global_load_lds_dwordx4 v[250:251], off
	v_add_u32_e32 v254, 0x2000, v155
	v_lshl_add_u64 v[252:253], v[134:135], 0, s[4:5]
	v_readfirstlane_b32 s26, v254
	v_lshl_add_u64 v[252:253], v[252:253], 0, s[10:11]
	s_mov_b32 m0, s26
	s_nop 0
	global_load_lds_dwordx4 v[252:253], off
	s_waitcnt vmcnt(6)
	s_waitcnt lgkmcnt(0)
	s_barrier
	s_setprio 1
	v_mfma_f32_16x16x32_bf16 v[60:63], v[170:173], v[186:189], v[60:63]
	v_mfma_f32_16x16x32_bf16 v[56:59], v[178:181], v[186:189], v[56:59]
	v_mfma_f32_16x16x32_bf16 v[52:55], v[170:173], v[196:199], v[52:55]
	v_mfma_f32_16x16x32_bf16 v[48:51], v[178:181], v[196:199], v[48:51]
	v_mfma_f32_16x16x32_bf16 v[44:47], v[170:173], v[204:207], v[44:47]
	v_mfma_f32_16x16x32_bf16 v[40:43], v[178:181], v[204:207], v[40:43]
	v_mfma_f32_16x16x32_bf16 v[36:39], v[170:173], v[212:215], v[36:39]
	v_mfma_f32_16x16x32_bf16 v[32:35], v[178:181], v[212:215], v[32:35]
	v_mfma_f32_16x16x32_bf16 v[60:63], v[174:177], v[190:193], v[60:63]
	v_mfma_f32_16x16x32_bf16 v[56:59], v[182:185], v[190:193], v[56:59]
	v_mfma_f32_16x16x32_bf16 v[52:55], v[174:177], v[200:203], v[52:55]
	v_mfma_f32_16x16x32_bf16 v[48:51], v[182:185], v[200:203], v[48:51]
	v_mfma_f32_16x16x32_bf16 v[44:47], v[174:177], v[208:211], v[44:47]
	v_mfma_f32_16x16x32_bf16 v[40:43], v[182:185], v[208:211], v[40:43]
	v_mfma_f32_16x16x32_bf16 v[36:39], v[174:177], v[216:219], v[36:39]
	v_mfma_f32_16x16x32_bf16 v[32:35], v[182:185], v[216:219], v[32:35]
	v_mfma_f32_16x16x32_bf16 v[28:31], v[220:223], v[186:189], v[28:31]
	v_mfma_f32_16x16x32_bf16 v[24:27], v[228:231], v[186:189], v[24:27]
	v_mfma_f32_16x16x32_bf16 v[20:23], v[220:223], v[196:199], v[20:23]
	v_mfma_f32_16x16x32_bf16 v[16:19], v[228:231], v[196:199], v[16:19]
	v_mfma_f32_16x16x32_bf16 v[12:15], v[220:223], v[204:207], v[12:15]
	v_mfma_f32_16x16x32_bf16 v[8:11], v[228:231], v[204:207], v[8:11]
	v_mfma_f32_16x16x32_bf16 v[4:7], v[220:223], v[212:215], v[4:7]
	v_mfma_f32_16x16x32_bf16 v[0:3], v[228:231], v[212:215], v[0:3]
	v_mfma_f32_16x16x32_bf16 v[28:31], v[224:227], v[190:193], v[28:31]
	v_mfma_f32_16x16x32_bf16 v[24:27], v[232:235], v[190:193], v[24:27]
	v_mfma_f32_16x16x32_bf16 v[20:23], v[224:227], v[200:203], v[20:23]
	v_mfma_f32_16x16x32_bf16 v[16:19], v[232:235], v[200:203], v[16:19]
	v_mfma_f32_16x16x32_bf16 v[12:15], v[224:227], v[208:211], v[12:15]
	v_mfma_f32_16x16x32_bf16 v[8:11], v[232:235], v[208:211], v[8:11]
	v_mfma_f32_16x16x32_bf16 v[4:7], v[224:227], v[216:219], v[4:7]
	v_mfma_f32_16x16x32_bf16 v[0:3], v[232:235], v[216:219], v[0:3]
	s_setprio 0
	s_barrier
	ds_read_b128 v[170:173], v156
	ds_read_b128 v[174:177], v156 offset:1024
	ds_read_b128 v[178:181], v156 offset:2048
	ds_read_b128 v[182:185], v156 offset:3072
	ds_read_b128 v[186:189], v146 offset:32768
	ds_read_b128 v[190:193], v146 offset:33792
	ds_read_b128 v[196:199], v143 offset:32768
	ds_read_b128 v[200:203], v143 offset:33792
	ds_read_b128 v[204:207], v142 offset:32768
	ds_read_b128 v[208:211], v142 offset:33792
	ds_read_b128 v[212:215], v141 offset:32768
	ds_read_b128 v[216:219], v141 offset:33792
	ds_read_b128 v[220:223], v154
	ds_read_b128 v[224:227], v154 offset:1024
	ds_read_b128 v[228:231], v154 offset:2048
	ds_read_b128 v[232:235], v154 offset:3072
	v_lshl_add_u64 v[250:251], v[136:137], 0, s[4:5]
	v_readfirstlane_b32 s26, v157
	v_lshl_add_u64 v[250:251], v[250:251], 0, s[10:11]
	s_mov_b32 m0, s26
	s_nop 0
	global_load_lds_dwordx4 v[250:251], off
	v_lshl_add_u64 v[252:253], v[138:139], 0, s[4:5]
	v_readfirstlane_b32 s26, v158
	v_lshl_add_u64 v[252:253], v[252:253], 0, s[10:11]
	s_mov_b32 m0, s26
	s_nop 0
	global_load_lds_dwordx4 v[252:253], off
	s_waitcnt lgkmcnt(0)
	s_barrier
; #define WAIT_V(n) asm volatile("s_waitcnt vmcnt(" #n ")" ::: "memory")
; #define WAIT_L(n) asm volatile("s_waitcnt lgkmcnt(" #n ")" ::: "memory")
; #define BAR __builtin_amdgcn_s_barrier()
; #define SCHED __builtin_amdgcn_sched_barrier(0)
;     ...
;       LDB(B0, 1, 0); SCHED; LDA(At, 1, 0); STAGE(SA(0, 1), A, brow + HALF, t + 2);
;       WAIT_L(8); BAR; WAIT_L(0); MMA(0, 0, At, B0); BAR; SCHED;
;       LDB(B1, 1, 1); STAGE(SB(1, 0), Bt, bcol, t + 3);
;       BAR; WAIT_L(0); MMA(0, 1, At, B1); BAR;
;       LDA(At, 1, 1); STAGE(SA(1, 0), A, brow, t + 3);
;       BAR; WAIT_L(0); MMA(1, 0, At, B0); BAR; SCHED;
;       STAGE(SB(1, 1), Bt, bcol + HALF, t + 3);
;       WAIT_V(6); BAR; MMA(1, 1, At, B1); BAR;
;     }
	s_setprio 1
	v_mfma_f32_16x16x32_bf16 v[124:127], v[170:173], v[186:189], v[124:127]
	v_mfma_f32_16x16x32_bf16 v[120:123], v[178:181], v[186:189], v[120:123]
	v_mfma_f32_16x16x32_bf16 v[116:119], v[170:173], v[196:199], v[116:119]
	v_mfma_f32_16x16x32_bf16 v[112:115], v[178:181], v[196:199], v[112:115]
	v_mfma_f32_16x16x32_bf16 v[108:111], v[170:173], v[204:207], v[108:111]
	v_mfma_f32_16x16x32_bf16 v[104:107], v[178:181], v[204:207], v[104:107]
	v_mfma_f32_16x16x32_bf16 v[100:103], v[170:173], v[212:215], v[100:103]
	v_mfma_f32_16x16x32_bf16 v[96:99], v[178:181], v[212:215], v[96:99]
	v_mfma_f32_16x16x32_bf16 v[124:127], v[174:177], v[190:193], v[124:127]
	v_mfma_f32_16x16x32_bf16 v[120:123], v[182:185], v[190:193], v[120:123]
	v_mfma_f32_16x16x32_bf16 v[116:119], v[174:177], v[200:203], v[116:119]
	v_mfma_f32_16x16x32_bf16 v[112:115], v[182:185], v[200:203], v[112:115]
	v_mfma_f32_16x16x32_bf16 v[108:111], v[174:177], v[208:211], v[108:111]
	v_mfma_f32_16x16x32_bf16 v[104:107], v[182:185], v[208:211], v[104:107]
	v_mfma_f32_16x16x32_bf16 v[100:103], v[174:177], v[216:219], v[100:103]
	v_mfma_f32_16x16x32_bf16 v[96:99], v[182:185], v[216:219], v[96:99]
	v_mfma_f32_16x16x32_bf16 v[92:95], v[220:223], v[186:189], v[92:95]
	v_mfma_f32_16x16x32_bf16 v[88:91], v[228:231], v[186:189], v[88:91]
	v_mfma_f32_16x16x32_bf16 v[84:87], v[220:223], v[196:199], v[84:87]
	v_mfma_f32_16x16x32_bf16 v[80:83], v[228:231], v[196:199], v[80:83]
	v_mfma_f32_16x16x32_bf16 v[76:79], v[220:223], v[204:207], v[76:79]
	v_mfma_f32_16x16x32_bf16 v[72:75], v[228:231], v[204:207], v[72:75]
	v_mfma_f32_16x16x32_bf16 v[68:71], v[220:223], v[212:215], v[68:71]
	v_mfma_f32_16x16x32_bf16 v[64:67], v[228:231], v[212:215], v[64:67]
	v_mfma_f32_16x16x32_bf16 v[92:95], v[224:227], v[190:193], v[92:95]
	v_mfma_f32_16x16x32_bf16 v[88:91], v[232:235], v[190:193], v[88:91]
	v_mfma_f32_16x16x32_bf16 v[84:87], v[224:227], v[200:203], v[84:87]
	v_mfma_f32_16x16x32_bf16 v[80:83], v[232:235], v[200:203], v[80:83]
	v_mfma_f32_16x16x32_bf16 v[76:79], v[224:227], v[208:211], v[76:79]
	v_mfma_f32_16x16x32_bf16 v[72:75], v[232:235], v[208:211], v[72:75]
	v_mfma_f32_16x16x32_bf16 v[68:71], v[224:227], v[216:219], v[68:71]
	v_mfma_f32_16x16x32_bf16 v[64:67], v[232:235], v[216:219], v[64:67]
	s_setprio 0
	s_barrier
	ds_read_b128 v[186:189], v146 offset:49152
	ds_read_b128 v[190:193], v146 offset:50176
	ds_read_b128 v[196:199], v143 offset:49152
	ds_read_b128 v[200:203], v143 offset:50176
	ds_read_b128 v[204:207], v142 offset:49152
	ds_read_b128 v[208:211], v142 offset:50176
	ds_read_b128 v[212:215], v141 offset:49152
	ds_read_b128 v[216:219], v141 offset:50176
	v_lshl_add_u64 v[250:251], v[132:133], 0, s[4:5]
	v_readfirstlane_b32 s26, v159
	v_lshl_add_u64 v[250:251], v[250:251], 0, s[12:13]
	s_mov_b32 m0, s26
	s_nop 0
	global_load_lds_dwordx4 v[250:251], off
	v_lshl_add_u64 v[252:253], v[134:135], 0, s[4:5]
	v_readfirstlane_b32 s26, v160
	v_lshl_add_u64 v[252:253], v[252:253], 0, s[12:13]
	s_mov_b32 m0, s26
	s_nop 0
	global_load_lds_dwordx4 v[252:253], off
	v_lshl_add_u64 v[250:251], v[136:137], 0, s[4:5]
	v_readfirstlane_b32 s26, v161
	v_lshl_add_u64 v[250:251], v[250:251], 0, s[12:13]
	s_mov_b32 m0, s26
	s_nop 0
	global_load_lds_dwordx4 v[250:251], off
	v_lshl_add_u64 v[252:253], v[138:139], 0, s[4:5]
	v_readfirstlane_b32 s26, v162
	v_lshl_add_u64 v[252:253], v[252:253], 0, s[12:13]
	s_mov_b32 m0, s26
	s_nop 0
	global_load_lds_dwordx4 v[252:253], off
	v_lshl_add_u64 v[250:251], v[132:133], 0, s[4:5]
	v_readfirstlane_b32 s26, v163
	v_lshl_add_u64 v[250:251], v[250:251], 0, s[14:15]
	s_mov_b32 m0, s26
	s_nop 0
	global_load_lds_dwordx4 v[250:251], off
	v_lshl_add_u64 v[252:253], v[134:135], 0, s[4:5]
	v_readfirstlane_b32 s26, v164
	v_lshl_add_u64 v[252:253], v[252:253], 0, s[14:15]
	s_mov_b32 m0, s26
	s_nop 0
	global_load_lds_dwordx4 v[252:253], off
	s_waitcnt vmcnt(6)
	s_waitcnt lgkmcnt(0)
	s_barrier
	s_setprio 1
	v_mfma_f32_16x16x32_bf16 v[60:63], v[170:173], v[186:189], v[60:63]
	v_mfma_f32_16x16x32_bf16 v[56:59], v[178:181], v[186:189], v[56:59]
	v_mfma_f32_16x16x32_bf16 v[52:55], v[170:173], v[196:199], v[52:55]
	v_mfma_f32_16x16x32_bf16 v[48:51], v[178:181], v[196:199], v[48:51]
	v_mfma_f32_16x16x32_bf16 v[44:47], v[170:173], v[204:207], v[44:47]
	v_mfma_f32_16x16x32_bf16 v[40:43], v[178:181], v[204:207], v[40:43]
	v_mfma_f32_16x16x32_bf16 v[36:39], v[170:173], v[212:215], v[36:39]
	v_mfma_f32_16x16x32_bf16 v[32:35], v[178:181], v[212:215], v[32:35]
	v_mfma_f32_16x16x32_bf16 v[60:63], v[174:177], v[190:193], v[60:63]
	v_mfma_f32_16x16x32_bf16 v[56:59], v[182:185], v[190:193], v[56:59]
	v_mfma_f32_16x16x32_bf16 v[52:55], v[174:177], v[200:203], v[52:55]
	v_mfma_f32_16x16x32_bf16 v[48:51], v[182:185], v[200:203], v[48:51]
	v_mfma_f32_16x16x32_bf16 v[44:47], v[174:177], v[208:211], v[44:47]
	v_mfma_f32_16x16x32_bf16 v[40:43], v[182:185], v[208:211], v[40:43]
	v_mfma_f32_16x16x32_bf16 v[36:39], v[174:177], v[216:219], v[36:39]
	v_mfma_f32_16x16x32_bf16 v[32:35], v[182:185], v[216:219], v[32:35]
	v_mfma_f32_16x16x32_bf16 v[28:31], v[220:223], v[186:189], v[28:31]
	v_mfma_f32_16x16x32_bf16 v[24:27], v[228:231], v[186:189], v[24:27]
	v_mfma_f32_16x16x32_bf16 v[20:23], v[220:223], v[196:199], v[20:23]
	v_mfma_f32_16x16x32_bf16 v[16:19], v[228:231], v[196:199], v[16:19]
	v_mfma_f32_16x16x32_bf16 v[12:15], v[220:223], v[204:207], v[12:15]
	v_mfma_f32_16x16x32_bf16 v[8:11], v[228:231], v[204:207], v[8:11]
	v_mfma_f32_16x16x32_bf16 v[4:7], v[220:223], v[212:215], v[4:7]
	v_mfma_f32_16x16x32_bf16 v[0:3], v[228:231], v[212:215], v[0:3]
	v_mfma_f32_16x16x32_bf16 v[28:31], v[224:227], v[190:193], v[28:31]
	v_mfma_f32_16x16x32_bf16 v[24:27], v[232:235], v[190:193], v[24:27]
	v_mfma_f32_16x16x32_bf16 v[20:23], v[224:227], v[200:203], v[20:23]
	v_mfma_f32_16x16x32_bf16 v[16:19], v[232:235], v[200:203], v[16:19]
	v_mfma_f32_16x16x32_bf16 v[12:15], v[224:227], v[208:211], v[12:15]
	v_mfma_f32_16x16x32_bf16 v[8:11], v[232:235], v[208:211], v[8:11]
	v_mfma_f32_16x16x32_bf16 v[4:7], v[224:227], v[216:219], v[4:7]
	v_mfma_f32_16x16x32_bf16 v[0:3], v[232:235], v[216:219], v[0:3]
	s_setprio 0
	s_add_i32 s25, s25, 2
	s_add_u32 s4, s4, 0x100
	s_addc_u32 s5, s5, 0
	s_cmp_gt_u32 s25, 27
	s_barrier
; #define WAIT_V(n) asm volatile("s_waitcnt vmcnt(" #n ")" ::: "memory")
; #define WAIT_L(n) asm volatile("s_waitcnt lgkmcnt(" #n ")" ::: "memory")
; #define BAR __builtin_amdgcn_s_barrier()
;     ...
;     { LDB(B0, 0, 0); LDA(At, 0, 0); STAGE(SA(1, 1), A, brow + HALF, nt - 1);
;       BAR; WAIT_L(0); MMA(0, 0, At, B0); BAR;
;       LDB(B1, 0, 1); BAR; WAIT_L(0); MMA(0, 1, At, B1); BAR;
;       LDA(At, 0, 1); WAIT_V(4); BAR; WAIT_L(0); MMA(1, 0, At, B0); MMA(1, 1, At, B1); BAR; }
;     { LDB(B0, 1, 0); LDA(At, 1, 0); WAIT_V(2); BAR; WAIT_L(0); MMA(0, 0, At, B0); BAR;
;       LDB(B1, 1, 1); WAIT_V(0); BAR; WAIT_L(0); MMA(0, 1, At, B1); BAR;
	s_cbranch_scc0 .LBB0_550
	v_readfirstlane_b32 s4, v167
	v_lshl_add_u64 v[128:129], v[128:129], 0, s[16:17]
	s_mov_b32 m0, s4
	v_readfirstlane_b32 s4, v168
	ds_read_b128 v[132:135], v166
	ds_read_b128 v[136:139], v166 offset:1024
	ds_read_b128 v[158:161], v166 offset:2048
	ds_read_b128 v[170:173], v166 offset:3072
	ds_read_b128 v[174:177], v146
	ds_read_b128 v[178:181], v146 offset:1024
	ds_read_b128 v[182:185], v143
	ds_read_b128 v[186:189], v143 offset:1024
	ds_read_b128 v[190:193], v142
	ds_read_b128 v[196:199], v142 offset:1024
	ds_read_b128 v[200:203], v141
	ds_read_b128 v[204:207], v141 offset:1024
	global_load_lds_dwordx4 v[128:129], off
	v_lshl_add_u64 v[128:129], v[130:131], 0, s[16:17]
	s_mov_b32 m0, s4
	s_nop 0
	global_load_lds_dwordx4 v[128:129], off
	s_barrier
	s_waitcnt lgkmcnt(0)
	s_setprio 1
	s_waitcnt lgkmcnt(0)
	v_mfma_f32_16x16x32_bf16 v[124:127], v[132:135], v[174:177], v[124:127]
	v_mfma_f32_16x16x32_bf16 v[120:123], v[158:161], v[174:177], v[120:123]
	v_mfma_f32_16x16x32_bf16 v[116:119], v[132:135], v[182:185], v[116:119]
	v_mfma_f32_16x16x32_bf16 v[112:115], v[158:161], v[182:185], v[112:115]
	v_mfma_f32_16x16x32_bf16 v[124:127], v[136:139], v[178:181], v[124:127]
	v_mfma_f32_16x16x32_bf16 v[120:123], v[170:173], v[178:181], v[120:123]
	v_mfma_f32_16x16x32_bf16 v[116:119], v[136:139], v[186:189], v[116:119]
	v_mfma_f32_16x16x32_bf16 v[112:115], v[170:173], v[186:189], v[112:115]
	v_mfma_f32_16x16x32_bf16 v[108:111], v[132:135], v[190:193], v[108:111]
	v_mfma_f32_16x16x32_bf16 v[104:107], v[158:161], v[190:193], v[104:107]
	v_mfma_f32_16x16x32_bf16 v[100:103], v[132:135], v[200:203], v[100:103]
	v_mfma_f32_16x16x32_bf16 v[96:99], v[158:161], v[200:203], v[96:99]
	v_mfma_f32_16x16x32_bf16 v[128:131], v[136:139], v[196:199], v[108:111]
	v_mfma_f32_16x16x32_bf16 v[166:169], v[170:173], v[196:199], v[104:107]
	v_mfma_f32_16x16x32_bf16 v[208:211], v[136:139], v[204:207], v[100:103]
	v_mfma_f32_16x16x32_bf16 v[212:215], v[170:173], v[204:207], v[96:99]
	s_setprio 0
	s_barrier
	s_nop 1
	ds_read_b128 v[96:99], v165
	ds_read_b128 v[100:103], v165 offset:1024
	ds_read_b128 v[104:107], v165 offset:2048
	ds_read_b128 v[108:111], v165 offset:3072
	s_barrier
	s_waitcnt lgkmcnt(0)
	s_setprio 1
	s_waitcnt lgkmcnt(0)
	v_mfma_f32_16x16x32_bf16 v[92:95], v[96:99], v[174:177], v[92:95]
	v_mfma_f32_16x16x32_bf16 v[88:91], v[104:107], v[174:177], v[88:91]
	v_mfma_f32_16x16x32_bf16 v[68:71], v[96:99], v[200:203], v[68:71]
	v_mfma_f32_16x16x32_bf16 v[64:67], v[104:107], v[200:203], v[64:67]
	v_mfma_f32_16x16x32_bf16 v[92:95], v[100:103], v[178:181], v[92:95]
	v_mfma_f32_16x16x32_bf16 v[88:91], v[108:111], v[178:181], v[88:91]
	v_mfma_f32_16x16x32_bf16 v[84:87], v[96:99], v[182:185], v[84:87]
	v_mfma_f32_16x16x32_bf16 v[80:83], v[104:107], v[182:185], v[80:83]
	v_mfma_f32_16x16x32_bf16 v[76:79], v[96:99], v[190:193], v[76:79]
	v_mfma_f32_16x16x32_bf16 v[72:75], v[104:107], v[190:193], v[72:75]
	v_mfma_f32_16x16x32_bf16 v[68:71], v[100:103], v[204:207], v[68:71]
	v_mfma_f32_16x16x32_bf16 v[64:67], v[108:111], v[204:207], v[64:67]
	v_mfma_f32_16x16x32_bf16 v[162:165], v[100:103], v[186:189], v[84:87]
	v_mfma_f32_16x16x32_bf16 v[174:177], v[108:111], v[186:189], v[80:83]
	v_mfma_f32_16x16x32_bf16 v[178:181], v[100:103], v[196:199], v[76:79]
	v_mfma_f32_16x16x32_bf16 v[182:185], v[108:111], v[196:199], v[72:75]
	s_setprio 0
	s_barrier
	s_nop 0
	ds_read_b128 v[72:75], v146 offset:16384
	ds_read_b128 v[76:79], v146 offset:17408
	ds_read_b128 v[80:83], v143 offset:16384
	ds_read_b128 v[84:87], v143 offset:17408
	ds_read_b128 v[186:189], v142 offset:16384
	ds_read_b128 v[190:193], v142 offset:17408
	ds_read_b128 v[196:199], v141 offset:16384
	ds_read_b128 v[200:203], v141 offset:17408
	s_waitcnt vmcnt(4)
	s_barrier
	s_waitcnt lgkmcnt(0)
	s_setprio 1
	s_waitcnt lgkmcnt(0)
	v_mfma_f32_16x16x32_bf16 v[60:63], v[132:135], v[72:75], v[60:63]
	v_mfma_f32_16x16x32_bf16 v[56:59], v[158:161], v[72:75], v[56:59]
	v_mfma_f32_16x16x32_bf16 v[44:47], v[132:135], v[186:189], v[44:47]
	v_mfma_f32_16x16x32_bf16 v[40:43], v[158:161], v[186:189], v[40:43]
	v_mfma_f32_16x16x32_bf16 v[60:63], v[136:139], v[76:79], v[60:63]
	v_mfma_f32_16x16x32_bf16 v[56:59], v[170:173], v[76:79], v[56:59]
	v_mfma_f32_16x16x32_bf16 v[52:55], v[132:135], v[80:83], v[52:55]
	v_mfma_f32_16x16x32_bf16 v[48:51], v[158:161], v[80:83], v[48:51]
	v_mfma_f32_16x16x32_bf16 v[44:47], v[136:139], v[190:193], v[44:47]
	v_mfma_f32_16x16x32_bf16 v[40:43], v[170:173], v[190:193], v[40:43]
	v_mfma_f32_16x16x32_bf16 v[36:39], v[132:135], v[196:199], v[36:39]
	v_mfma_f32_16x16x32_bf16 v[32:35], v[158:161], v[196:199], v[32:35]
	v_mfma_f32_16x16x32_bf16 v[204:207], v[136:139], v[84:87], v[52:55]
	v_mfma_f32_16x16x32_bf16 v[216:219], v[170:173], v[84:87], v[48:51]
	v_mfma_f32_16x16x32_bf16 v[132:135], v[136:139], v[200:203], v[36:39]
	v_mfma_f32_16x16x32_bf16 v[136:139], v[170:173], v[200:203], v[32:35]
	s_setprio 0
	s_setprio 1
	v_mfma_f32_16x16x32_bf16 v[28:31], v[96:99], v[72:75], v[28:31]
	v_mfma_f32_16x16x32_bf16 v[24:27], v[104:107], v[72:75], v[24:27]
	v_mfma_f32_16x16x32_bf16 v[12:15], v[96:99], v[186:189], v[12:15]
	v_mfma_f32_16x16x32_bf16 v[4:7], v[96:99], v[196:199], v[4:7]
	v_mfma_f32_16x16x32_bf16 v[28:31], v[100:103], v[76:79], v[28:31]
	v_mfma_f32_16x16x32_bf16 v[24:27], v[108:111], v[76:79], v[24:27]
	v_mfma_f32_16x16x32_bf16 v[20:23], v[96:99], v[80:83], v[20:23]
	v_mfma_f32_16x16x32_bf16 v[16:19], v[104:107], v[80:83], v[16:19]
	v_mfma_f32_16x16x32_bf16 v[12:15], v[100:103], v[190:193], v[12:15]
	v_mfma_f32_16x16x32_bf16 v[8:11], v[104:107], v[186:189], v[8:11]
	v_mfma_f32_16x16x32_bf16 v[4:7], v[100:103], v[200:203], v[4:7]
	v_mfma_f32_16x16x32_bf16 v[0:3], v[104:107], v[196:199], v[0:3]
	v_mfma_f32_16x16x32_bf16 v[158:161], v[100:103], v[84:87], v[20:23]
	v_mfma_f32_16x16x32_bf16 v[170:173], v[108:111], v[84:87], v[16:19]
	v_mfma_f32_16x16x32_bf16 v[186:189], v[108:111], v[190:193], v[8:11]
	v_mfma_f32_16x16x32_bf16 v[190:193], v[108:111], v[200:203], v[0:3]
	s_setprio 0
	s_barrier
; #define WAIT_V(n) asm volatile("s_waitcnt vmcnt(" #n ")" ::: "memory")
; #define WAIT_L(n) asm volatile("s_waitcnt lgkmcnt(" #n ")" ::: "memory")
; #define BAR __builtin_amdgcn_s_barrier()
;     ...
;     { LDB(B0, 1, 0); LDA(At, 1, 0); WAIT_V(2); BAR; WAIT_L(0); MMA(0, 0, At, B0); BAR;
;       LDB(B1, 1, 1); WAIT_V(0); BAR; WAIT_L(0); MMA(0, 1, At, B1); BAR;
;       LDA(At, 1, 1); BAR; WAIT_L(0); MMA(1, 0, At, B0); MMA(1, 1, At, B1); BAR; }
;     if (wr == 0) BAR;
;     ...
;           if (MODE == 3) {
;             const long row = brow + rloc;
;             const float4 s0 = *(const float4*)(ssq + row * 8), s1 = *(const float4*)(ssq + row * 8 + 4);
;             rscale = rsqrtf((s0.x + s0.y + s0.z + s0.w + s1.x + s1.y + s1.z + s1.w) * (1.f / DM) + EPS);
	s_nop 1
	ds_read_b128 v[0:3], v156
	ds_read_b128 v[8:11], v156 offset:1024
	ds_read_b128 v[196:199], v156 offset:2048
	ds_read_b128 v[200:203], v156 offset:3072
	ds_read_b128 v[16:19], v146 offset:32768
	ds_read_b128 v[20:23], v146 offset:33792
	ds_read_b128 v[32:35], v143 offset:32768
	ds_read_b128 v[36:39], v143 offset:33792
	ds_read_b128 v[48:51], v142 offset:32768
	ds_read_b128 v[52:55], v142 offset:33792
	ds_read_b128 v[220:223], v141 offset:32768
	ds_read_b128 v[224:227], v141 offset:33792
	s_waitcnt vmcnt(2)
	s_barrier
	s_waitcnt lgkmcnt(0)
	s_setprio 1
	s_waitcnt lgkmcnt(0)
	v_mfma_f32_16x16x32_bf16 v[72:75], v[0:3], v[16:19], v[124:127]
	v_mfma_f32_16x16x32_bf16 v[104:107], v[8:11], v[20:23], v[72:75]
	v_mfma_f32_16x16x32_bf16 v[72:75], v[196:199], v[16:19], v[120:123]
	v_mfma_f32_16x16x32_bf16 v[108:111], v[200:203], v[20:23], v[72:75]
	v_mfma_f32_16x16x32_bf16 v[72:75], v[0:3], v[32:35], v[116:119]
	v_mfma_f32_16x16x32_bf16 v[96:99], v[8:11], v[36:39], v[72:75]
	v_mfma_f32_16x16x32_bf16 v[72:75], v[196:199], v[32:35], v[112:115]
	v_mfma_f32_16x16x32_bf16 v[100:103], v[200:203], v[36:39], v[72:75]
	v_mfma_f32_16x16x32_bf16 v[72:75], v[0:3], v[48:51], v[128:131]
	v_mfma_f32_16x16x32_bf16 v[84:87], v[8:11], v[52:55], v[72:75]
	v_mfma_f32_16x16x32_bf16 v[72:75], v[196:199], v[48:51], v[166:169]
	v_mfma_f32_16x16x32_bf16 v[80:83], v[200:203], v[52:55], v[72:75]
	v_mfma_f32_16x16x32_bf16 v[72:75], v[0:3], v[220:223], v[208:211]
	v_mfma_f32_16x16x32_bf16 v[76:79], v[8:11], v[224:227], v[72:75]
	v_mfma_f32_16x16x32_bf16 v[72:75], v[196:199], v[220:223], v[212:215]
	v_mfma_f32_16x16x32_bf16 v[72:75], v[200:203], v[224:227], v[72:75]
	s_setprio 0
	s_barrier
	ds_read_b128 v[128:131], v154
	ds_read_b128 v[166:169], v154 offset:1024
	ds_read_b128 v[208:211], v154 offset:2048
	ds_read_b128 v[154:157], v154 offset:3072
	s_waitcnt vmcnt(0)
	v_readlane_b32 s64, v248, 0
	v_readlane_b32 s65, v248, 1
	v_and_b32_e32 v249, 0xff, v194
	v_add_u32_e32 v249, s24, v249
	v_lshlrev_b32_e32 v249, 5, v249
	v_lshrrev_b32_e32 v250, 8, v194
	v_lshl_add_u32 v249, v250, 4, v249
	s_nop 1
	global_load_dwordx4 v[250:253], v249, s[64:65]
	s_barrier
	s_waitcnt lgkmcnt(0)
	s_setprio 1
	s_waitcnt lgkmcnt(0)
	v_mfma_f32_16x16x32_bf16 v[92:95], v[128:131], v[16:19], v[92:95]
	v_mfma_f32_16x16x32_bf16 v[16:19], v[208:211], v[16:19], v[88:91]
	v_mfma_f32_16x16x32_bf16 v[124:127], v[154:157], v[20:23], v[16:19]
	v_mfma_f32_16x16x32_bf16 v[16:19], v[128:131], v[32:35], v[162:165]
	v_mfma_f32_16x16x32_bf16 v[112:115], v[166:169], v[36:39], v[16:19]
	v_mfma_f32_16x16x32_bf16 v[16:19], v[208:211], v[32:35], v[174:177]
	v_mfma_f32_16x16x32_bf16 v[116:119], v[154:157], v[36:39], v[16:19]
	v_mfma_f32_16x16x32_bf16 v[16:19], v[128:131], v[48:51], v[178:181]
	v_mfma_f32_16x16x32_bf16 v[120:123], v[166:169], v[20:23], v[92:95]
	v_mfma_f32_16x16x32_bf16 v[92:95], v[166:169], v[52:55], v[16:19]
	v_mfma_f32_16x16x32_bf16 v[16:19], v[208:211], v[48:51], v[182:185]
	v_mfma_f32_16x16x32_bf16 v[88:91], v[154:157], v[52:55], v[16:19]
	v_mfma_f32_16x16x32_bf16 v[16:19], v[128:131], v[220:223], v[68:71]
	v_mfma_f32_16x16x32_bf16 v[68:71], v[166:169], v[224:227], v[16:19]
	v_mfma_f32_16x16x32_bf16 v[16:19], v[208:211], v[220:223], v[64:67]
	v_mfma_f32_16x16x32_bf16 v[64:67], v[154:157], v[224:227], v[16:19]
	s_setprio 0
	s_barrier
	ds_read_b128 v[162:165], v146 offset:49152
	ds_read_b128 v[174:177], v146 offset:50176
	ds_read_b128 v[178:181], v143 offset:49152
	ds_read_b128 v[182:185], v143 offset:50176
	ds_read_b128 v[212:215], v142 offset:49152
	ds_read_b128 v[220:223], v142 offset:50176
	ds_read_b128 v[224:227], v141 offset:49152
	ds_read_b128 v[140:143], v141 offset:50176
	s_barrier
	s_waitcnt lgkmcnt(0)
	s_setprio 1
	s_waitcnt lgkmcnt(0)
	v_mfma_f32_16x16x32_bf16 v[16:19], v[0:3], v[162:165], v[60:63]
	v_mfma_f32_16x16x32_bf16 v[52:55], v[8:11], v[174:177], v[16:19]
	v_mfma_f32_16x16x32_bf16 v[16:19], v[196:199], v[162:165], v[56:59]
	v_mfma_f32_16x16x32_bf16 v[48:51], v[200:203], v[174:177], v[16:19]
	v_mfma_f32_16x16x32_bf16 v[16:19], v[0:3], v[178:181], v[204:207]
	v_mfma_f32_16x16x32_bf16 v[36:39], v[8:11], v[182:185], v[16:19]
	v_mfma_f32_16x16x32_bf16 v[16:19], v[196:199], v[178:181], v[216:219]
	v_mfma_f32_16x16x32_bf16 v[32:35], v[200:203], v[182:185], v[16:19]
	v_mfma_f32_16x16x32_bf16 v[16:19], v[0:3], v[212:215], v[44:47]
	v_mfma_f32_16x16x32_bf16 v[0:3], v[0:3], v[224:227], v[132:135]
	v_mfma_f32_16x16x32_bf16 v[20:23], v[8:11], v[220:223], v[16:19]
	v_mfma_f32_16x16x32_bf16 v[16:19], v[196:199], v[212:215], v[40:43]
	v_mfma_f32_16x16x32_bf16 v[8:11], v[8:11], v[140:143], v[0:3]
	v_mfma_f32_16x16x32_bf16 v[0:3], v[196:199], v[224:227], v[136:139]
	v_mfma_f32_16x16x32_bf16 v[16:19], v[200:203], v[220:223], v[16:19]
	v_mfma_f32_16x16x32_bf16 v[0:3], v[200:203], v[140:143], v[0:3]
	s_setprio 0
	s_setprio 1
	v_mfma_f32_16x16x32_bf16 v[24:27], v[208:211], v[162:165], v[24:27]
	v_mfma_f32_16x16x32_bf16 v[28:31], v[128:131], v[162:165], v[28:31]
	v_mfma_f32_16x16x32_bf16 v[56:59], v[154:157], v[174:177], v[24:27]
	v_mfma_f32_16x16x32_bf16 v[24:27], v[128:131], v[178:181], v[158:161]
	v_mfma_f32_16x16x32_bf16 v[12:15], v[128:131], v[212:215], v[12:15]
	v_mfma_f32_16x16x32_bf16 v[60:63], v[166:169], v[174:177], v[28:31]
	v_mfma_f32_16x16x32_bf16 v[44:47], v[166:169], v[182:185], v[24:27]
	v_mfma_f32_16x16x32_bf16 v[24:27], v[208:211], v[178:181], v[170:173]
	v_mfma_f32_16x16x32_bf16 v[28:31], v[166:169], v[220:223], v[12:15]
	v_mfma_f32_16x16x32_bf16 v[12:15], v[208:211], v[212:215], v[186:189]
	v_mfma_f32_16x16x32_bf16 v[4:7], v[128:131], v[224:227], v[4:7]
	v_mfma_f32_16x16x32_bf16 v[40:43], v[154:157], v[182:185], v[24:27]
	v_mfma_f32_16x16x32_bf16 v[24:27], v[154:157], v[220:223], v[12:15]
	v_mfma_f32_16x16x32_bf16 v[12:15], v[166:169], v[140:143], v[4:7]
	v_mfma_f32_16x16x32_bf16 v[4:7], v[208:211], v[224:227], v[190:193]
	v_mfma_f32_16x16x32_bf16 v[4:7], v[154:157], v[140:143], v[4:7]
	s_setprio 0
	v_cmp_gt_u32_e32 vcc, s34, v144
	s_barrier
	s_and_saveexec_b64 s[4:5], vcc
	s_cbranch_execz .LBB0_542
	s_barrier
	s_branch .LBB0_542
.Lp6_exit:
	v_readlane_b32 s62, v255, 12
	v_readlane_b32 s63, v255, 13
	v_readlane_b32 s64, v255, 14
	v_readlane_b32 s65, v255, 15
	v_readlane_b32 s66, v255, 16
	v_readlane_b32 s67, v255, 17
	v_readlane_b32 s68, v255, 18
	v_readlane_b32 s69, v255, 19
	v_readlane_b32 s70, v255, 20
	v_readlane_b32 s71, v255, 21
	v_readlane_b32 s72, v255, 22
	v_readlane_b32 s73, v255, 23
	s_nop 3
